# gather attention: each query's 1 KB output row written with one global_store_dwordx4 per wave (transposed through the idle V staging area) instead of 16 two-byte stores
# baseline (speedup 1.0000x reference)
; #define LAS __attribute__((address_space(3)))
; #define G_KLOAD(dst, SELP, kb0, cnt) do { _Pragma("unroll") for (int i_ = 0; i_ < (cnt); ++i_) { const int s_ = (SELP)[16 * ((kb0) + i_) + n]; const bf16_t* kp_ = Zb + (size_t)s_ * NZ + ZDK + g * 8; \
;         dst[2 * i_] = *(const bf16x8*)kp_; dst[2 * i_ + 1] = *(const bf16x8*)(kp_ + 32); } asm volatile("" ::: "memory"); } while (0)
; #define G_S(src, kb0, cnt) do { _Pragma("unroll") for (int i_ = 0; i_ < (cnt); ++i_) { f32x4 acc_ = {0.f, 0.f, 0.f, 0.f}; acc_ = mfma16(src[2 * i_], qf0, acc_); acc_ = mfma16(src[2 * i_ + 1], qf1, acc_); sc[(kb0) + i_] = acc_; } } while (0)
; __device__ __forceinline__ void dsa_unit(const Params& p, LAS unsigned char* lds, int b, int c) {
;     ...
;     __syncthreads();
;     const int n = lane & 15, g = lane >> 4, trq = (lane & 15) >> 2, trp = lane & 3;
;     LAS unsigned char* vst = lds + DS_VST + wid * 8192;
;     ...
;     bf16x8 kA[8], qfn0, qfn1;
;     { LAS const unsigned short* sel0 = selall + wid * 256; G_KLOAD(kA, sel0, 0, 4);
;       const bf16_t* qp = Z + (rowb + t0 + wid) * NZ + ZDQ + (n & 7) * 64 + g * 8; qfn0 = *(const bf16x8*)qp; qfn1 = *(const bf16x8*)(qp + 32); }
; #pragma unroll 1
;     for (int qi = 0; qi < 8; ++qi) {
;         const int ql = wid + 8 * qi; const size_t row = rowb + t0 + ql;
;         LAS const unsigned short* sel = selall + ql * 256;
;         const bf16x8 qf0 = qfn0, qf1 = qfn1;
;         bf16x8 kB[8], kC[8], kD[8]; f32x4 sc[16];
;         G_KLOAD(kB, sel, 4, 4);
;         G_S(kA, 0, 4);
;         G_KLOAD(kC, sel, 8, 4);
;         G_S(kB, 4, 4);
;         G_KLOAD(kD, sel, 12, 4);
;         G_S(kC, 8, 4);
;         G_S(kD, 12, 4);
.LBB0_1820:
	s_lshl_b32 s3, s69, 9
	v_add_u32_e32 v0, s3, v209
	s_waitcnt lgkmcnt(0)
	s_barrier
	ds_read_u16 v1, v0
	ds_read_u16 v2, v0 offset:32
	ds_read_u16 v6, v0 offset:64
	ds_read_u16 v7, v0 offset:96
	v_lshlrev_b32_e32 v172, 1, v158
	v_mov_b32_e32 v173, v155
	s_waitcnt lgkmcnt(3)
	v_mul_u32_u24_e32 v154, 0x2400, v1
	s_waitcnt lgkmcnt(2)
	v_mul_u32_u24_e32 v0, 0x2400, v2
	v_lshl_add_u64 v[2:3], s[36:37], 0, v[154:155]
	v_lshl_add_u64 v[2:3], v[2:3], 0, v[172:173]
	v_mov_b32_e32 v1, v155
	v_lshl_add_u64 v[4:5], v[2:3], 0, s[38:39]
	v_add_co_u32_e32 v2, vcc, s66, v2
	v_lshl_add_u64 v[0:1], s[36:37], 0, v[0:1]
	s_nop 0
	v_addc_co_u32_e32 v3, vcc, 0, v3, vcc
	v_lshl_add_u64 v[0:1], v[0:1], 0, v[172:173]
	global_load_dwordx4 v[16:19], v[2:3], off
	global_load_dwordx4 v[20:23], v[4:5], off offset:64
	v_lshl_add_u64 v[2:3], v[0:1], 0, s[38:39]
	v_add_co_u32_e32 v0, vcc, s66, v0
	s_waitcnt lgkmcnt(1)
	v_mul_u32_u24_e32 v154, 0x2400, v6
	v_addc_co_u32_e32 v1, vcc, 0, v1, vcc
	global_load_dwordx4 v[8:11], v[0:1], off
	global_load_dwordx4 v[12:15], v[2:3], off offset:64
	v_lshl_add_u64 v[2:3], s[36:37], 0, v[154:155]
	s_waitcnt lgkmcnt(0)
	v_mul_u32_u24_e32 v0, 0x2400, v7
	v_lshl_add_u64 v[2:3], v[2:3], 0, v[172:173]
	v_mov_b32_e32 v1, v155
	s_lshl_b32 s0, s69, 13
	v_lshl_add_u64 v[4:5], v[2:3], 0, s[38:39]
	v_add_co_u32_e32 v2, vcc, s66, v2
	v_lshl_add_u64 v[0:1], s[36:37], 0, v[0:1]
	s_min_i32 s2, s2, 0x100
	v_addc_co_u32_e32 v3, vcc, 0, v3, vcc
	v_lshl_add_u64 v[0:1], v[0:1], 0, v[172:173]
	s_add_i32 s18, s0, 0x100
	global_load_dwordx4 v[32:35], v[2:3], off
	global_load_dwordx4 v[36:39], v[4:5], off offset:64
	v_lshl_add_u64 v[2:3], v[0:1], 0, s[38:39]
	v_add_co_u32_e32 v0, vcc, s66, v0
	s_add_u32 s0, s34, s69
	s_nop 0
	v_addc_co_u32_e32 v1, vcc, 0, v1, vcc
	s_addc_u32 s1, s35, 0
	global_load_dwordx4 v[40:43], v[0:1], off
	global_load_dwordx4 v[44:47], v[2:3], off offset:64
	s_mul_i32 s19, s1, 0x2400
	v_mad_u64_u32 v[0:1], s[0:1], s0, v223, v[160:161]
	v_add_u32_e32 v1, s19, v1
	global_load_dwordx4 v[4:7], v[0:1], off offset:3072
	s_nop 0
	global_load_dwordx4 v[0:3], v[0:1], off offset:3136
	s_add_u32 s0, s34, s69
	s_addc_u32 s1, s35, 0
	v_add_u32_e32 v24, s18, v211
	v_add_u32_e32 v25, s18, v188
	s_lshl_b64 s[0:1], s[0:1], 10
	s_mov_b32 s20, 0
	v_sub_u32_e32 v165, s2, v210
	v_add_u32_e32 v167, s3, v217
	v_lshl_add_u64 v[174:175], v[162:163], 0, s[0:1]
	v_add_u32_e32 v169, s3, v218
	v_add_u32_e32 v176, v24, v212
	v_add_u32_e32 v177, v25, v213
	v_mbcnt_lo_u32_b32 v241, -1, 0
	v_mbcnt_hi_u32_b32 v241, -1, v241
	v_lshrrev_b32_e32 v242, 4, v241
	v_and_b32_e32 v243, 15, v241
	v_lshlrev_b32_e32 v241, 4, v241
	v_lshl_add_u32 v243, v243, 1, v176
	v_lshl_add_u32 v243, v242, 9, v243
	v_sub_u32_e32 v243, v243, v241
	s_branch .LBB0_1822
.LBB0_1821:
	s_or_b64 exec, exec, s[0:1]
	v_readfirstlane_b32 s98, v174
	v_readfirstlane_b32 s99, v175
	s_waitcnt lgkmcnt(0)
	ds_read_b128 v[56:59], v176
	s_nop 3
	s_waitcnt lgkmcnt(0)
	global_store_dwordx4 v241, v[56:59], s[98:99] offset:-256
	s_addk_i32 s20, 0x1000
	s_mov_b64 s[0:1], 0x2000
	s_cmpk_lg_u32 s20, 0x8000
	v_lshl_add_u64 v[174:175], v[174:175], 0, s[0:1]
	s_cbranch_scc0 .LBB0_966
.LBB0_1822:
	v_add_u32_e32 v104, s20, v167
	v_add_u32_e32 v24, 0x10180, v104
	ds_read_u16 v24, v24
	v_add_u32_e32 v25, 0x101a0, v104
	ds_read_u16 v25, v25
	s_waitcnt vmcnt(1)
	v_mfma_f32_16x16x32_bf16 v[16:19], v[16:19], v[4:7], 0
	v_add_u32_e32 v178, s20, v169
	s_waitcnt lgkmcnt(1)
	v_mul_u32_u24_e32 v154, 0x2400, v24
	v_lshl_add_u64 v[26:27], s[36:37], 0, v[154:155]
	s_waitcnt lgkmcnt(0)
	v_mul_u32_u24_e32 v24, 0x2400, v25
	v_lshl_add_u64 v[26:27], v[26:27], 0, v[172:173]
	v_mov_b32_e32 v25, v155
	v_lshl_add_u64 v[28:29], v[26:27], 0, s[38:39]
	v_add_co_u32_e32 v26, vcc, s66, v26
	v_lshl_add_u64 v[24:25], s[36:37], 0, v[24:25]
	s_nop 0
	v_addc_co_u32_e32 v27, vcc, 0, v27, vcc
	v_lshl_add_u64 v[24:25], v[24:25], 0, v[172:173]
	global_load_dwordx4 v[64:67], v[26:27], off
	global_load_dwordx4 v[68:71], v[28:29], off offset:64
	v_lshl_add_u64 v[26:27], v[24:25], 0, s[38:39]
	v_add_co_u32_e32 v24, vcc, s66, v24
	v_mfma_f32_16x16x32_bf16 v[8:11], v[8:11], v[4:7], 0
	s_nop 0
	v_addc_co_u32_e32 v25, vcc, 0, v25, vcc
	global_load_dwordx4 v[56:59], v[24:25], off
	global_load_dwordx4 v[48:51], v[26:27], off offset:64
	v_add_u32_e32 v24, 0x101c0, v104
	ds_read_u16 v24, v24
	v_add_u32_e32 v25, 0x101e0, v104
	ds_read_u16 v25, v25
	s_waitcnt vmcnt(4)
	v_mfma_f32_16x16x32_bf16 v[20:23], v[20:23], v[0:3], v[16:19]
	v_mov_b32_e32 v171, v155
	s_waitcnt lgkmcnt(1)
	v_mul_u32_u24_e32 v154, 0x2400, v24
	v_lshl_add_u64 v[26:27], s[36:37], 0, v[154:155]
	v_lshl_add_u64 v[26:27], v[26:27], 0, v[172:173]
	v_lshl_add_u64 v[28:29], v[26:27], 0, s[38:39]
	v_add_co_u32_e32 v26, vcc, s66, v26
	s_waitcnt lgkmcnt(0)
	v_mul_u32_u24_e32 v24, 0x2400, v25
	v_addc_co_u32_e32 v27, vcc, 0, v27, vcc
	v_mov_b32_e32 v25, v155
	global_load_dwordx4 v[84:87], v[26:27], off
	global_load_dwordx4 v[80:83], v[28:29], off offset:64
	v_lshl_add_u64 v[24:25], s[36:37], 0, v[24:25]
	v_lshl_add_u64 v[24:25], v[24:25], 0, v[172:173]
	v_lshl_add_u64 v[26:27], v[24:25], 0, s[38:39]
	v_add_co_u32_e32 v24, vcc, s66, v24
	v_mfma_f32_16x16x32_bf16 v[16:19], v[12:15], v[0:3], v[8:11]
	s_nop 0
	v_addc_co_u32_e32 v25, vcc, 0, v25, vcc
	global_load_dwordx4 v[76:79], v[24:25], off
	global_load_dwordx4 v[72:75], v[26:27], off offset:64
	v_add_u32_e32 v24, 0x10200, v104
	ds_read_u16 v24, v24
	v_add_u32_e32 v25, 0x10220, v104
	ds_read_u16 v25, v25
	v_mfma_f32_16x16x32_bf16 v[8:11], v[32:35], v[4:7], 0
	v_mov_b32_e32 v33, v155
	s_waitcnt lgkmcnt(1)
	v_mul_u32_u24_e32 v154, 0x2400, v24
	v_mov_b32_e32 v140, v165
	s_waitcnt lgkmcnt(0)
; #define G_KLOAD(dst, SELP, kb0, cnt) do { _Pragma("unroll") for (int i_ = 0; i_ < (cnt); ++i_) { const int s_ = (SELP)[16 * ((kb0) + i_) + n]; const bf16_t* kp_ = Zb + (size_t)s_ * NZ + ZDK + g * 8; \
;         dst[2 * i_] = *(const bf16x8*)kp_; dst[2 * i_ + 1] = *(const bf16x8*)(kp_ + 32); } asm volatile("" ::: "memory"); } while (0)
; #define G_S(src, kb0, cnt) do { _Pragma("unroll") for (int i_ = 0; i_ < (cnt); ++i_) { f32x4 acc_ = {0.f, 0.f, 0.f, 0.f}; acc_ = mfma16(src[2 * i_], qf0, acc_); acc_ = mfma16(src[2 * i_ + 1], qf1, acc_); sc[(kb0) + i_] = acc_; } } while (0)
; __device__ __forceinline__ void dsa_unit(const Params& p, LAS unsigned char* lds, int b, int c) {
;     ...
;         G_KLOAD(kB, sel, 4, 4);
;         G_S(kA, 0, 4);
;         G_KLOAD(kC, sel, 8, 4);
;         G_S(kB, 4, 4);
;         G_KLOAD(kD, sel, 12, 4);
;         G_S(kC, 8, 4);
;         G_S(kD, 12, 4);
	v_mul_u32_u24_e32 v32, 0x2400, v25
	v_lshl_add_u64 v[24:25], s[36:37], 0, v[154:155]
	v_lshl_add_u64 v[24:25], v[24:25], 0, v[172:173]
	v_lshl_add_u64 v[26:27], v[24:25], 0, s[38:39]
	v_add_co_u32_e32 v24, vcc, s66, v24
	v_lshl_add_u64 v[32:33], s[36:37], 0, v[32:33]
	s_nop 0
	v_addc_co_u32_e32 v25, vcc, 0, v25, vcc
	v_lshl_add_u64 v[32:33], v[32:33], 0, v[172:173]
	v_lshl_add_u64 v[34:35], v[32:33], 0, s[38:39]
	v_add_co_u32_e32 v32, vcc, s66, v32
	global_load_dwordx4 v[28:31], v[24:25], off
	s_nop 0
	global_load_dwordx4 v[24:27], v[26:27], off offset:64
	v_addc_co_u32_e32 v33, vcc, 0, v33, vcc
	global_load_dwordx4 v[60:63], v[32:33], off
	global_load_dwordx4 v[52:55], v[34:35], off offset:64
	v_add_u32_e32 v32, 0x10240, v104
	ds_read_u16 v32, v32
	v_add_u32_e32 v33, 0x10260, v104
	ds_read_u16 v33, v33
	v_mfma_f32_16x16x32_bf16 v[12:15], v[36:39], v[0:3], v[8:11]
	s_movk_i32 s1, 0x41
	s_waitcnt lgkmcnt(1)
	v_mul_u32_u24_e32 v154, 0x2400, v32
	v_lshl_add_u64 v[34:35], s[36:37], 0, v[154:155]
	v_lshl_add_u64 v[34:35], v[34:35], 0, v[172:173]
	v_lshl_add_u64 v[36:37], v[34:35], 0, s[38:39]
	v_add_co_u32_e32 v34, vcc, s66, v34
	s_waitcnt lgkmcnt(0)
	v_mul_u32_u24_e32 v32, 0x2400, v33
	v_addc_co_u32_e32 v35, vcc, 0, v35, vcc
	v_mov_b32_e32 v33, v155
	v_mfma_f32_16x16x32_bf16 v[8:11], v[40:43], v[4:7], 0
	global_load_dwordx4 v[100:103], v[34:35], off
	global_load_dwordx4 v[96:99], v[36:37], off offset:64
	v_lshl_add_u64 v[32:33], s[36:37], 0, v[32:33]
	v_lshl_add_u64 v[32:33], v[32:33], 0, v[172:173]
	s_waitcnt vmcnt(11)
	v_mfma_f32_16x16x32_bf16 v[36:39], v[56:59], v[4:7], 0
	v_lshl_add_u64 v[34:35], v[32:33], 0, s[38:39]
	v_add_co_u32_e32 v32, vcc, s66, v32
	v_mfma_f32_16x16x32_bf16 v[8:11], v[44:47], v[0:3], v[8:11]
	s_nop 0
	v_addc_co_u32_e32 v33, vcc, 0, v33, vcc
	global_load_dwordx4 v[92:95], v[32:33], off
	global_load_dwordx4 v[88:91], v[34:35], off offset:64
	s_waitcnt vmcnt(12)
	v_mfma_f32_16x16x32_bf16 v[44:47], v[48:51], v[0:3], v[36:39]
	v_add_u32_e32 v48, 0x10280, v104
	ds_read_u16 v48, v48
	v_add_u32_e32 v49, 0x102a0, v104
	ds_read_u16 v49, v49
	s_waitcnt vmcnt(11)
	v_mfma_f32_16x16x32_bf16 v[36:39], v[84:87], v[4:7], 0
	s_waitcnt lgkmcnt(1)
	v_mul_u32_u24_e32 v154, 0x2400, v48
	v_lshl_add_u64 v[50:51], s[36:37], 0, v[154:155]
	s_waitcnt lgkmcnt(0)
	v_mul_u32_u24_e32 v48, 0x2400, v49
	v_mfma_f32_16x16x32_bf16 v[32:35], v[64:67], v[4:7], 0
	v_lshl_add_u64 v[50:51], v[50:51], 0, v[172:173]
	v_mov_b32_e32 v49, v155
	v_lshl_add_u64 v[56:57], v[50:51], 0, s[38:39]
	s_waitcnt vmcnt(10)
	v_mfma_f32_16x16x32_bf16 v[40:43], v[80:83], v[0:3], v[36:39]
	v_add_co_u32_e32 v50, vcc, s66, v50
	v_lshl_add_u64 v[48:49], s[36:37], 0, v[48:49]
	s_waitcnt vmcnt(9)
	v_mfma_f32_16x16x32_bf16 v[36:39], v[76:79], v[4:7], 0
	v_addc_co_u32_e32 v51, vcc, 0, v51, vcc
	v_lshl_add_u64 v[48:49], v[48:49], 0, v[172:173]
	v_mfma_f32_16x16x32_bf16 v[32:35], v[68:71], v[0:3], v[32:35]
	global_load_dwordx4 v[68:71], v[50:51], off
	global_load_dwordx4 v[64:67], v[56:57], off offset:64
	v_lshl_add_u64 v[50:51], v[48:49], 0, s[38:39]
	v_add_co_u32_e32 v48, vcc, s66, v48
	s_waitcnt vmcnt(10)
	v_mfma_f32_16x16x32_bf16 v[36:39], v[72:75], v[0:3], v[36:39]
	v_addc_co_u32_e32 v49, vcc, 0, v49, vcc
	v_add_u32_e32 v72, 0x102c0, v104
	global_load_dwordx4 v[56:59], v[48:49], off
	s_nop 0
	global_load_dwordx4 v[48:51], v[50:51], off offset:64
	ds_read_u16 v72, v72
	v_add_u32_e32 v73, 0x102e0, v104
	ds_read_u16 v73, v73
	v_mov_b32_e32 v77, v155
	s_waitcnt vmcnt(11)
	v_mfma_f32_16x16x32_bf16 v[28:31], v[28:31], v[4:7], 0
	s_waitcnt lgkmcnt(1)
	v_mul_u32_u24_e32 v154, 0x2400, v72
	s_waitcnt lgkmcnt(0)
	v_mul_u32_u24_e32 v76, 0x2400, v73
	v_lshl_add_u64 v[72:73], s[36:37], 0, v[154:155]
	v_lshl_add_u64 v[72:73], v[72:73], 0, v[172:173]
	v_lshl_add_u64 v[74:75], v[72:73], 0, s[38:39]
	v_add_co_u32_e32 v72, vcc, s66, v72
	v_lshl_add_u64 v[76:77], s[36:37], 0, v[76:77]
	s_nop 0
	v_addc_co_u32_e32 v73, vcc, 0, v73, vcc
	v_lshl_add_u64 v[76:77], v[76:77], 0, v[172:173]
	v_lshl_add_u64 v[78:79], v[76:77], 0, s[38:39]
	v_add_co_u32_e32 v76, vcc, s66, v76
	global_load_dwordx4 v[84:87], v[72:73], off
	s_nop 0
	global_load_dwordx4 v[72:75], v[74:75], off offset:64
	v_addc_co_u32_e32 v77, vcc, 0, v77, vcc
	global_load_dwordx4 v[80:83], v[76:77], off
	s_nop 0
	global_load_dwordx4 v[76:79], v[78:79], off offset:64
	s_waitcnt vmcnt(14)
	v_mfma_f32_16x16x32_bf16 v[128:131], v[24:27], v[0:3], v[28:31]
	v_and_b32_e32 v179, 64, v186
	s_mov_b32 s0, s69
	s_waitcnt vmcnt(13)
	v_mfma_f32_16x16x32_bf16 v[24:27], v[60:63], v[4:7], 0
	s_add_i32 s69, s69, 8
	s_waitcnt vmcnt(12)
	v_mfma_f32_16x16x32_bf16 v[120:123], v[52:55], v[0:3], v[24:27]
	s_waitcnt vmcnt(11)
	v_mfma_f32_16x16x32_bf16 v[24:27], v[100:103], v[4:7], 0
	s_waitcnt vmcnt(10)
	v_mfma_f32_16x16x32_bf16 v[116:119], v[96:99], v[0:3], v[24:27]
	s_waitcnt vmcnt(9)
	v_mfma_f32_16x16x32_bf16 v[24:27], v[92:95], v[4:7], 0
	s_waitcnt vmcnt(8)
	v_mfma_f32_16x16x32_bf16 v[124:127], v[88:91], v[0:3], v[24:27]
	s_waitcnt vmcnt(7)
	v_mfma_f32_16x16x32_bf16 v[24:27], v[68:71], v[4:7], 0
	s_waitcnt vmcnt(6)
	v_mfma_f32_16x16x32_bf16 v[112:115], v[64:67], v[0:3], v[24:27]
	s_waitcnt vmcnt(5)
	v_mfma_f32_16x16x32_bf16 v[24:27], v[56:59], v[4:7], 0
	s_waitcnt vmcnt(4)
	v_mfma_f32_16x16x32_bf16 v[100:103], v[48:51], v[0:3], v[24:27]
	s_waitcnt vmcnt(3)
	v_mfma_f32_16x16x32_bf16 v[24:27], v[84:87], v[4:7], 0
	s_waitcnt vmcnt(1)
	v_mfma_f32_16x16x32_bf16 v[4:7], v[80:83], v[4:7], 0
	v_mfma_f32_16x16x32_bf16 v[96:99], v[72:75], v[0:3], v[24:27]
	s_waitcnt vmcnt(0)
; #define G_VLOAD(dst, ch) do { _Pragma("unroll") for (int i_ = 0; i_ < 8; ++i_) { const int pc_ = lane + 64 * i_, rowi_ = pc_ >> 3, c16_ = pc_ & 7; const int s_ = sel[64 * (ch) + rowi_]; \
;         dst[i_] = *(const u32x4*)(Zb + (size_t)s_ * NZ + ZDV + c16_ * 8); } asm volatile("" ::: "memory"); } while (0)
; __device__ __forceinline__ void dsa_unit(const Params& p, LAS unsigned char* lds, int b, int c) {
;     ...
;         G_VLOAD(vrA, 0); G_VLOAD(vrB, 1);
	v_mfma_f32_16x16x32_bf16 v[0:3], v[76:79], v[0:3], v[4:7]
	s_nop 4
	v_add_u32_e32 v4, 0x10100, v178
	ds_read_u16 v4, v4
	v_add_u32_e32 v5, 0x10110, v178
	ds_read_u16 v5, v5
	s_waitcnt lgkmcnt(1)
	v_mul_u32_u24_e32 v154, 0x2400, v4
	v_lshl_add_u64 v[6:7], s[36:37], 0, v[154:155]
	s_waitcnt lgkmcnt(0)
	v_mul_u32_u24_e32 v4, 0x2400, v5
	v_lshl_add_u64 v[6:7], v[6:7], 0, v[170:171]
	v_mov_b32_e32 v5, v155
	v_add_co_u32_e32 v6, vcc, s66, v6
	v_lshl_add_u64 v[4:5], s[36:37], 0, v[4:5]
	s_nop 0
	v_addc_co_u32_e32 v7, vcc, 0, v7, vcc
	v_lshl_add_u64 v[4:5], v[4:5], 0, v[170:171]
	v_add_co_u32_e32 v4, vcc, s66, v4
	global_load_dwordx4 v[64:67], v[6:7], off offset:128
	s_nop 0
	v_addc_co_u32_e32 v5, vcc, 0, v5, vcc
	global_load_dwordx4 v[68:71], v[4:5], off offset:128
	v_add_u32_e32 v4, 0x10120, v178
	ds_read_u16 v4, v4
	v_add_u32_e32 v5, 0x10130, v178
	ds_read_u16 v5, v5
	s_waitcnt lgkmcnt(1)
	v_mul_u32_u24_e32 v154, 0x2400, v4
	v_lshl_add_u64 v[6:7], s[36:37], 0, v[154:155]
	s_waitcnt lgkmcnt(0)
	v_mul_u32_u24_e32 v4, 0x2400, v5
	v_lshl_add_u64 v[6:7], v[6:7], 0, v[170:171]
	v_mov_b32_e32 v5, v155
	v_add_co_u32_e32 v6, vcc, s66, v6
	v_lshl_add_u64 v[4:5], s[36:37], 0, v[4:5]
	s_nop 0
	v_addc_co_u32_e32 v7, vcc, 0, v7, vcc
	v_lshl_add_u64 v[4:5], v[4:5], 0, v[170:171]
	v_add_co_u32_e32 v4, vcc, s66, v4
	global_load_dwordx4 v[72:75], v[6:7], off offset:128
	s_nop 0
	v_addc_co_u32_e32 v5, vcc, 0, v5, vcc
	global_load_dwordx4 v[76:79], v[4:5], off offset:128
	v_add_u32_e32 v4, 0x10140, v178
	ds_read_u16 v4, v4
	v_add_u32_e32 v5, 0x10150, v178
	ds_read_u16 v5, v5
	s_waitcnt lgkmcnt(1)
	v_mul_u32_u24_e32 v154, 0x2400, v4
	v_lshl_add_u64 v[6:7], s[36:37], 0, v[154:155]
	s_waitcnt lgkmcnt(0)
	v_mul_u32_u24_e32 v4, 0x2400, v5
	v_lshl_add_u64 v[6:7], v[6:7], 0, v[170:171]
	v_mov_b32_e32 v5, v155
	v_add_co_u32_e32 v6, vcc, s66, v6
	v_lshl_add_u64 v[4:5], s[36:37], 0, v[4:5]
	s_nop 0
	v_addc_co_u32_e32 v7, vcc, 0, v7, vcc
	v_lshl_add_u64 v[4:5], v[4:5], 0, v[170:171]
	v_add_co_u32_e32 v4, vcc, s66, v4
	global_load_dwordx4 v[80:83], v[6:7], off offset:128
	s_nop 0
	v_addc_co_u32_e32 v5, vcc, 0, v5, vcc
	global_load_dwordx4 v[84:87], v[4:5], off offset:128
	v_add_u32_e32 v4, 0x10160, v178
	ds_read_u16 v4, v4
	v_add_u32_e32 v5, 0x10170, v178
	ds_read_u16 v5, v5
	s_waitcnt lgkmcnt(1)
	v_mul_u32_u24_e32 v154, 0x2400, v4
	v_lshl_add_u64 v[6:7], s[36:37], 0, v[154:155]
	s_waitcnt lgkmcnt(0)
	v_mul_u32_u24_e32 v4, 0x2400, v5
	v_lshl_add_u64 v[6:7], v[6:7], 0, v[170:171]
	v_mov_b32_e32 v5, v155
	v_add_co_u32_e32 v6, vcc, s66, v6
	v_lshl_add_u64 v[4:5], s[36:37], 0, v[4:5]
	s_nop 0
	v_addc_co_u32_e32 v7, vcc, 0, v7, vcc
	v_lshl_add_u64 v[4:5], v[4:5], 0, v[170:171]
	v_add_co_u32_e32 v4, vcc, s66, v4
	global_load_dwordx4 v[104:107], v[6:7], off offset:128
	s_nop 0
	v_addc_co_u32_e32 v5, vcc, 0, v5, vcc
	global_load_dwordx4 v[108:111], v[4:5], off offset:128
	v_add_u32_e32 v4, 0x10180, v178
	ds_read_u16 v4, v4
	v_add_u32_e32 v5, 0x10190, v178
	ds_read_u16 v5, v5
	s_waitcnt lgkmcnt(1)
	v_mul_u32_u24_e32 v154, 0x2400, v4
	v_lshl_add_u64 v[6:7], s[36:37], 0, v[154:155]
	s_waitcnt lgkmcnt(0)
	v_mul_u32_u24_e32 v4, 0x2400, v5
	v_lshl_add_u64 v[6:7], v[6:7], 0, v[170:171]
	v_mov_b32_e32 v5, v155
	v_add_co_u32_e32 v6, vcc, s66, v6
	v_lshl_add_u64 v[4:5], s[36:37], 0, v[4:5]
	s_nop 0
	v_addc_co_u32_e32 v7, vcc, 0, v7, vcc
	v_lshl_add_u64 v[4:5], v[4:5], 0, v[170:171]
	v_add_co_u32_e32 v4, vcc, s66, v4
	global_load_dwordx4 v[24:27], v[6:7], off offset:128
	s_nop 0
	v_addc_co_u32_e32 v5, vcc, 0, v5, vcc
	global_load_dwordx4 v[28:31], v[4:5], off offset:128
	v_add_u32_e32 v4, 0x101a0, v178
	ds_read_u16 v4, v4
	v_add_u32_e32 v5, 0x101b0, v178
	ds_read_u16 v5, v5
	s_waitcnt lgkmcnt(1)
	v_mul_u32_u24_e32 v154, 0x2400, v4
	v_lshl_add_u64 v[6:7], s[36:37], 0, v[154:155]
	s_waitcnt lgkmcnt(0)
	v_mul_u32_u24_e32 v4, 0x2400, v5
	v_lshl_add_u64 v[6:7], v[6:7], 0, v[170:171]
	v_mov_b32_e32 v5, v155
	v_add_co_u32_e32 v6, vcc, s66, v6
	v_lshl_add_u64 v[4:5], s[36:37], 0, v[4:5]
	s_nop 0
	v_addc_co_u32_e32 v7, vcc, 0, v7, vcc
	v_lshl_add_u64 v[4:5], v[4:5], 0, v[170:171]
	v_add_co_u32_e32 v4, vcc, s66, v4
	global_load_dwordx4 v[48:51], v[6:7], off offset:128
	s_nop 0
	v_addc_co_u32_e32 v5, vcc, 0, v5, vcc
	global_load_dwordx4 v[52:55], v[4:5], off offset:128
	v_add_u32_e32 v4, 0x101c0, v178
	ds_read_u16 v4, v4
	v_add_u32_e32 v5, 0x101d0, v178
	ds_read_u16 v5, v5
	s_waitcnt lgkmcnt(1)
	v_mul_u32_u24_e32 v154, 0x2400, v4
	v_lshl_add_u64 v[6:7], s[36:37], 0, v[154:155]
	s_waitcnt lgkmcnt(0)
	v_mul_u32_u24_e32 v4, 0x2400, v5
	v_lshl_add_u64 v[6:7], v[6:7], 0, v[170:171]
	v_mov_b32_e32 v5, v155
	v_add_co_u32_e32 v6, vcc, s66, v6
	v_lshl_add_u64 v[4:5], s[36:37], 0, v[4:5]
	s_nop 0
	v_addc_co_u32_e32 v7, vcc, 0, v7, vcc
	v_lshl_add_u64 v[4:5], v[4:5], 0, v[170:171]
	v_add_co_u32_e32 v4, vcc, s66, v4
	global_load_dwordx4 v[56:59], v[6:7], off offset:128
	s_nop 0
	v_addc_co_u32_e32 v5, vcc, 0, v5, vcc
	global_load_dwordx4 v[60:63], v[4:5], off offset:128
	v_add_u32_e32 v4, 0x101e0, v178
	ds_read_u16 v4, v4
	v_add_u32_e32 v5, 0x101f0, v178
	ds_read_u16 v5, v5
	s_waitcnt lgkmcnt(1)
	v_mul_u32_u24_e32 v154, 0x2400, v4
	v_lshl_add_u64 v[6:7], s[36:37], 0, v[154:155]
	s_waitcnt lgkmcnt(0)
; __device__ __forceinline__ void dsa_unit(const Params& p, LAS unsigned char* lds, int b, int c) {
;     ...
;         float mx = -INFINITY; int nlim = nsel - 4 * g; asm volatile("" : "+v"(nlim));
; #pragma unroll
;         for (int kb = 0; kb < 16; ++kb)
; #pragma unroll
;             for (int i = 0; i < 4; ++i) { if (16 * kb + i >= nlim) sc[kb][i] = -INFINITY; mx = fmaxf(mx, sc[kb][i]); }
	v_mul_u32_u24_e32 v4, 0x2400, v5
	v_lshl_add_u64 v[6:7], v[6:7], 0, v[170:171]
	v_mov_b32_e32 v5, v155
	v_add_co_u32_e32 v6, vcc, s66, v6
	v_lshl_add_u64 v[4:5], s[36:37], 0, v[4:5]
	s_nop 0
	v_addc_co_u32_e32 v7, vcc, 0, v7, vcc
	v_lshl_add_u64 v[4:5], v[4:5], 0, v[170:171]
	v_add_co_u32_e32 v4, vcc, s66, v4
	global_load_dwordx4 v[88:91], v[6:7], off offset:128
	s_nop 0
	v_addc_co_u32_e32 v5, vcc, 0, v5, vcc
	global_load_dwordx4 v[92:95], v[4:5], off offset:128
	v_mov_b32_e32 v4, s67
	v_cmp_lt_i32_e32 vcc, 0, v140
	v_cmp_lt_i32_e64 s[2:3], 2, v140
	v_cmp_lt_i32_e64 s[18:19], 3, v140
	v_cndmask_b32_e32 v4, v4, v20, vcc
	v_cmp_lt_i32_e32 vcc, 1, v140
	v_cndmask_b32_e64 v7, v226, v22, s[2:3]
	s_or_b64 s[2:3], s[18:19], s[2:3]
	v_cndmask_b32_e32 v5, v226, v21, vcc
	s_or_b64 vcc, s[2:3], vcc
	v_max3_f32 v6, v4, s67, v5
	v_cndmask_b32_e64 v132, v5, v21, s[2:3]
	v_cndmask_b32_e64 v21, v7, v22, s[18:19]
	v_cndmask_b32_e32 v141, v4, v20, vcc
	v_cndmask_b32_e64 v22, v226, v23, s[18:19]
	v_cmp_lt_i32_e32 vcc, 16, v140
	v_mov_b32_e32 v4, s67
	v_cmp_lt_i32_e64 s[2:3], 18, v140
	v_cmp_lt_i32_e64 s[18:19], 19, v140
	v_max3_f32 v5, v6, v7, v22
	v_cndmask_b32_e32 v4, v4, v16, vcc
	v_cmp_lt_i32_e32 vcc, 17, v140
	v_cndmask_b32_e64 v7, v226, v18, s[2:3]
	s_or_b64 s[2:3], s[18:19], s[2:3]
	v_cndmask_b32_e32 v6, v226, v17, vcc
	s_or_b64 vcc, s[2:3], vcc
	v_max3_f32 v5, v5, v4, v6
	v_cndmask_b32_e64 v134, v6, v17, s[2:3]
	v_cndmask_b32_e64 v133, v7, v18, s[18:19]
	v_cndmask_b32_e32 v142, v4, v16, vcc
	v_cndmask_b32_e64 v135, v226, v19, s[18:19]
	v_cmp_lt_i32_e32 vcc, 32, v140
	v_mov_b32_e32 v4, s67
	v_cmp_lt_i32_e64 s[2:3], 34, v140
	v_cmp_lt_i32_e64 s[18:19], 35, v140
	v_max3_f32 v5, v5, v7, v135
	v_cndmask_b32_e32 v4, v4, v12, vcc
	v_cmp_lt_i32_e32 vcc, 33, v140
	v_cndmask_b32_e64 v7, v226, v14, s[2:3]
	s_or_b64 s[2:3], s[18:19], s[2:3]
	v_cndmask_b32_e32 v6, v226, v13, vcc
	s_or_b64 vcc, s[2:3], vcc
	v_max3_f32 v5, v5, v4, v6
	v_cndmask_b32_e64 v138, v6, v13, s[2:3]
	v_cndmask_b32_e64 v136, v7, v14, s[18:19]
	v_cndmask_b32_e32 v143, v4, v12, vcc
	v_cndmask_b32_e64 v139, v226, v15, s[18:19]
	v_cmp_lt_i32_e32 vcc, 48, v140
	v_mov_b32_e32 v4, s67
	v_cmp_lt_i32_e64 s[2:3], 50, v140
	v_cmp_lt_i32_e64 s[18:19], 51, v140
	v_max3_f32 v5, v5, v7, v139
	v_cndmask_b32_e32 v4, v4, v8, vcc
	v_cmp_lt_i32_e32 vcc, 49, v140
	v_cndmask_b32_e64 v7, v226, v10, s[2:3]
	s_or_b64 s[2:3], s[18:19], s[2:3]
	v_cndmask_b32_e32 v6, v226, v9, vcc
	s_or_b64 vcc, s[2:3], vcc
	v_max3_f32 v5, v5, v4, v6
	v_cndmask_b32_e32 v181, v4, v8, vcc
	v_cmp_lt_i32_e32 vcc, 64, v140
	v_mov_b32_e32 v4, s67
	v_cndmask_b32_e64 v154, v6, v9, s[2:3]
	v_cndmask_b32_e32 v4, v4, v32, vcc
	v_cmp_lt_i32_e32 vcc, s1, v140
	s_movk_i32 s1, 0x42
	v_cmp_lt_i32_e64 s[2:3], s1, v140
	s_movk_i32 s1, 0x43
	v_cndmask_b32_e64 v180, v7, v10, s[18:19]
	v_cndmask_b32_e64 v182, v226, v11, s[18:19]
	v_cmp_lt_i32_e64 s[18:19], s1, v140
	v_max3_f32 v5, v5, v7, v182
	v_cndmask_b32_e64 v7, v226, v34, s[2:3]
	s_or_b64 s[2:3], s[18:19], s[2:3]
	v_cndmask_b32_e32 v6, v226, v33, vcc
	s_or_b64 vcc, s[2:3], vcc
	s_movk_i32 s1, 0x50
	v_max3_f32 v5, v5, v4, v6
	v_cndmask_b32_e32 v228, v4, v32, vcc
	v_cmp_lt_i32_e32 vcc, s1, v140
	v_mov_b32_e32 v4, s67
	s_movk_i32 s1, 0x51
	v_cndmask_b32_e32 v4, v4, v44, vcc
	v_cmp_lt_i32_e32 vcc, s1, v140
	s_movk_i32 s1, 0x52
	v_cndmask_b32_e64 v227, v6, v33, s[2:3]
	v_cmp_lt_i32_e64 s[2:3], s1, v140
	s_movk_i32 s1, 0x53
	v_cndmask_b32_e64 v183, v7, v34, s[18:19]
	v_cndmask_b32_e64 v137, v226, v35, s[18:19]
	v_cmp_lt_i32_e64 s[18:19], s1, v140
	v_max3_f32 v5, v5, v7, v137
	v_cndmask_b32_e64 v7, v226, v46, s[2:3]
	s_or_b64 s[2:3], s[18:19], s[2:3]
	v_cndmask_b32_e32 v6, v226, v45, vcc
	s_or_b64 vcc, s[2:3], vcc
	s_movk_i32 s1, 0x60
	v_max3_f32 v5, v5, v4, v6
	v_cndmask_b32_e32 v229, v4, v44, vcc
	v_cmp_lt_i32_e32 vcc, s1, v140
	v_mov_b32_e32 v4, s67
	s_movk_i32 s1, 0x61
	v_cndmask_b32_e32 v4, v4, v40, vcc
	v_cmp_lt_i32_e32 vcc, s1, v140
	s_movk_i32 s1, 0x62
	v_cndmask_b32_e64 v45, v6, v45, s[2:3]
	v_cmp_lt_i32_e64 s[2:3], s1, v140
	s_movk_i32 s1, 0x63
	v_cndmask_b32_e64 v46, v7, v46, s[18:19]
	v_cndmask_b32_e64 v35, v226, v47, s[18:19]
	v_cmp_lt_i32_e64 s[18:19], s1, v140
	v_max3_f32 v5, v5, v7, v35
	v_cndmask_b32_e64 v7, v226, v42, s[2:3]
	s_or_b64 s[2:3], s[18:19], s[2:3]
	v_cndmask_b32_e32 v6, v226, v41, vcc
	s_or_b64 vcc, s[2:3], vcc
	s_movk_i32 s1, 0x70
	v_max3_f32 v5, v5, v4, v6
	v_cndmask_b32_e32 v230, v4, v40, vcc
	v_cmp_lt_i32_e32 vcc, s1, v140
	v_mov_b32_e32 v4, s67
	s_movk_i32 s1, 0x71
	v_cndmask_b32_e32 v4, v4, v36, vcc
	v_cmp_lt_i32_e32 vcc, s1, v140
	s_movk_i32 s1, 0x72
	v_cndmask_b32_e64 v47, v6, v41, s[2:3]
	v_cmp_lt_i32_e64 s[2:3], s1, v140
	s_movk_i32 s1, 0x73
	v_cndmask_b32_e64 v42, v7, v42, s[18:19]
	v_cndmask_b32_e64 v23, v226, v43, s[18:19]
	v_cmp_lt_i32_e64 s[18:19], s1, v140
	v_max3_f32 v5, v5, v7, v23
	v_cndmask_b32_e64 v7, v226, v38, s[2:3]
	s_or_b64 s[2:3], s[18:19], s[2:3]
	v_cndmask_b32_e32 v6, v226, v37, vcc
	s_or_b64 vcc, s[2:3], vcc
	v_max3_f32 v5, v5, v4, v6
	v_cndmask_b32_e32 v231, v4, v36, vcc
	v_cmp_lt_i32_e32 vcc, s55, v140
	v_mov_b32_e32 v4, s67
	s_movk_i32 s1, 0x81
	v_cndmask_b32_e32 v4, v4, v128, vcc
	v_cmp_lt_i32_e32 vcc, s1, v140
	s_movk_i32 s1, 0x82
	v_cndmask_b32_e64 v43, v6, v37, s[2:3]
	v_cmp_lt_i32_e64 s[2:3], s1, v140
	s_movk_i32 s1, 0x83
	v_cndmask_b32_e64 v32, v7, v38, s[18:19]
	v_cndmask_b32_e64 v19, v226, v39, s[18:19]
	v_cmp_lt_i32_e64 s[18:19], s1, v140
	v_max3_f32 v5, v5, v7, v19
	v_cndmask_b32_e64 v7, v226, v130, s[2:3]
	s_or_b64 s[2:3], s[18:19], s[2:3]
	v_cndmask_b32_e32 v6, v226, v129, vcc
	s_or_b64 vcc, s[2:3], vcc
	s_movk_i32 s1, 0x90
; __device__ __forceinline__ void dsa_unit(const Params& p, LAS unsigned char* lds, int b, int c) {
;     ...
;         float mx = -INFINITY; int nlim = nsel - 4 * g; asm volatile("" : "+v"(nlim));
; #pragma unroll
;         for (int kb = 0; kb < 16; ++kb)
; #pragma unroll
;             for (int i = 0; i < 4; ++i) { if (16 * kb + i >= nlim) sc[kb][i] = -INFINITY; mx = fmaxf(mx, sc[kb][i]); }
;         mx = fmaxf(mx, __shfl_xor(mx, 16)); mx = fmaxf(mx, __shfl_xor(mx, 32));
	v_max3_f32 v5, v5, v4, v6
	v_cndmask_b32_e32 v128, v4, v128, vcc
	v_cmp_lt_i32_e32 vcc, s1, v140
	v_mov_b32_e32 v4, s67
	s_movk_i32 s1, 0x91
	v_cndmask_b32_e32 v4, v4, v120, vcc
	v_cmp_lt_i32_e32 vcc, s1, v140
	s_movk_i32 s1, 0x92
	v_cndmask_b32_e64 v40, v6, v129, s[2:3]
	v_cmp_lt_i32_e64 s[2:3], s1, v140
	s_movk_i32 s1, 0x93
	v_cndmask_b32_e64 v18, v7, v130, s[18:19]
	v_cndmask_b32_e64 v15, v226, v131, s[18:19]
	v_cmp_lt_i32_e64 s[18:19], s1, v140
	v_max3_f32 v5, v5, v7, v15
	v_cndmask_b32_e64 v7, v226, v122, s[2:3]
	s_or_b64 s[2:3], s[18:19], s[2:3]
	v_cndmask_b32_e32 v6, v226, v121, vcc
	s_or_b64 vcc, s[2:3], vcc
	s_movk_i32 s1, 0xa0
	v_max3_f32 v5, v5, v4, v6
	v_cndmask_b32_e32 v120, v4, v120, vcc
	v_cmp_lt_i32_e32 vcc, s1, v140
	v_mov_b32_e32 v4, s67
	s_movk_i32 s1, 0xa1
	v_cndmask_b32_e32 v4, v4, v116, vcc
	v_cmp_lt_i32_e32 vcc, s1, v140
	s_movk_i32 s1, 0xa2
	v_cndmask_b32_e64 v38, v6, v121, s[2:3]
	v_cmp_lt_i32_e64 s[2:3], s1, v140
	s_movk_i32 s1, 0xa3
	v_cndmask_b32_e64 v16, v7, v122, s[18:19]
	v_cndmask_b32_e64 v12, v226, v123, s[18:19]
	v_cmp_lt_i32_e64 s[18:19], s1, v140
	v_max3_f32 v5, v5, v7, v12
	v_cndmask_b32_e64 v7, v226, v118, s[2:3]
	s_or_b64 s[2:3], s[18:19], s[2:3]
	v_cndmask_b32_e32 v6, v226, v117, vcc
	s_or_b64 vcc, s[2:3], vcc
	s_movk_i32 s1, 0xb0
	v_max3_f32 v5, v5, v4, v6
	v_cndmask_b32_e32 v116, v4, v116, vcc
	v_cmp_lt_i32_e32 vcc, s1, v140
	v_mov_b32_e32 v4, s67
	s_movk_i32 s1, 0xb1
	v_cndmask_b32_e32 v4, v4, v124, vcc
	v_cmp_lt_i32_e32 vcc, s1, v140
	s_movk_i32 s1, 0xb2
	v_cndmask_b32_e64 v36, v6, v117, s[2:3]
	v_cmp_lt_i32_e64 s[2:3], s1, v140
	s_movk_i32 s1, 0xb3
	v_cndmask_b32_e64 v13, v7, v118, s[18:19]
	v_cndmask_b32_e64 v10, v226, v119, s[18:19]
	v_cmp_lt_i32_e64 s[18:19], s1, v140
	v_max3_f32 v5, v5, v7, v10
	v_cndmask_b32_e64 v7, v226, v126, s[2:3]
	s_or_b64 s[2:3], s[18:19], s[2:3]
	v_cndmask_b32_e32 v6, v226, v125, vcc
	s_or_b64 vcc, s[2:3], vcc
	s_movk_i32 s1, 0xc0
	v_max3_f32 v5, v5, v4, v6
	v_cndmask_b32_e32 v117, v4, v124, vcc
	v_cmp_lt_i32_e32 vcc, s1, v140
	v_mov_b32_e32 v4, s67
	s_movk_i32 s1, 0xc1
	v_cndmask_b32_e32 v4, v4, v112, vcc
	v_cmp_lt_i32_e32 vcc, s1, v140
	s_movk_i32 s1, 0xc2
	v_cndmask_b32_e64 v33, v6, v125, s[2:3]
	v_cmp_lt_i32_e64 s[2:3], s1, v140
	s_movk_i32 s1, 0xc3
	v_cndmask_b32_e64 v11, v7, v126, s[18:19]
	v_cndmask_b32_e64 v8, v226, v127, s[18:19]
	v_cmp_lt_i32_e64 s[18:19], s1, v140
	v_max3_f32 v5, v5, v7, v8
	v_cndmask_b32_e64 v7, v226, v114, s[2:3]
	s_or_b64 s[2:3], s[18:19], s[2:3]
	v_cndmask_b32_e32 v6, v226, v113, vcc
	s_or_b64 vcc, s[2:3], vcc
	s_movk_i32 s1, 0xd0
	v_max3_f32 v5, v5, v4, v6
	v_cndmask_b32_e32 v41, v4, v112, vcc
	v_cmp_lt_i32_e32 vcc, s1, v140
	v_mov_b32_e32 v4, s67
	s_movk_i32 s1, 0xd1
	v_cndmask_b32_e32 v4, v4, v100, vcc
	v_cmp_lt_i32_e32 vcc, s1, v140
	s_movk_i32 s1, 0xd2
	v_cndmask_b32_e64 v20, v6, v113, s[2:3]
	v_cmp_lt_i32_e64 s[2:3], s1, v140
	s_movk_i32 s1, 0xd3
	v_cndmask_b32_e64 v9, v7, v114, s[18:19]
	v_cndmask_b32_e64 v6, v226, v115, s[18:19]
	v_cmp_lt_i32_e64 s[18:19], s1, v140
	v_cndmask_b32_e64 v34, v226, v102, s[2:3]
	s_or_b64 s[2:3], s[18:19], s[2:3]
	v_max3_f32 v5, v5, v7, v6
	v_cndmask_b32_e32 v14, v226, v101, vcc
	s_or_b64 vcc, s[2:3], vcc
	s_movk_i32 s1, 0xe0
	v_max3_f32 v5, v5, v4, v14
	v_cndmask_b32_e64 v17, v14, v101, s[2:3]
	v_cndmask_b32_e32 v39, v4, v100, vcc
	v_cndmask_b32_e64 v4, v226, v103, s[18:19]
	v_cmp_lt_i32_e32 vcc, s1, v140
	v_mov_b32_e32 v14, s67
	s_movk_i32 s1, 0xe1
	v_cndmask_b32_e64 v7, v34, v102, s[18:19]
	v_max3_f32 v5, v5, v34, v4
	v_cndmask_b32_e32 v34, v14, v96, vcc
	v_cmp_lt_i32_e32 vcc, s1, v140
	s_movk_i32 s1, 0xe2
	v_cmp_lt_i32_e64 s[2:3], s1, v140
	s_movk_i32 s1, 0xe3
	v_cmp_lt_i32_e64 s[18:19], s1, v140
	v_cndmask_b32_e64 v100, v226, v98, s[2:3]
	s_or_b64 s[2:3], s[18:19], s[2:3]
	v_cndmask_b32_e32 v14, v226, v97, vcc
	s_or_b64 vcc, s[2:3], vcc
	v_max3_f32 v44, v5, v34, v14
	v_cndmask_b32_e32 v37, v34, v96, vcc
	v_cndmask_b32_e64 v34, v226, v99, s[18:19]
	s_movk_i32 s1, 0xf0
	v_max3_f32 v96, v44, v100, v34
	v_cmp_lt_i32_e32 vcc, s1, v140
	v_mov_b32_e32 v44, s67
	s_movk_i32 s1, 0xf1
	v_cndmask_b32_e32 v44, v44, v0, vcc
	v_cmp_lt_i32_e32 vcc, s1, v140
	s_movk_i32 s1, 0xf2
	v_cndmask_b32_e64 v14, v14, v97, s[2:3]
	v_cmp_lt_i32_e64 s[2:3], s1, v140
	s_movk_i32 s1, 0xf3
	v_cndmask_b32_e64 v5, v100, v98, s[18:19]
	v_cmp_lt_i32_e64 s[18:19], s1, v140
	v_cndmask_b32_e32 v97, v226, v1, vcc
	v_cndmask_b32_e64 v98, v226, v2, s[2:3]
	s_or_b64 s[2:3], s[18:19], s[2:3]
	v_max3_f32 v96, v96, v44, v97
	s_or_b64 vcc, s[2:3], vcc
	v_cndmask_b32_e64 v3, v226, v3, s[18:19]
	v_cndmask_b32_e64 v1, v97, v1, s[2:3]
	v_cndmask_b32_e32 v0, v44, v0, vcc
	v_max3_f32 v44, v96, v98, v3
	v_xor_b32_e32 v96, 16, v186
	v_add_u32_e32 v97, 64, v179
	v_cmp_lt_i32_e32 vcc, v96, v97
	v_cndmask_b32_e64 v2, v98, v2, s[18:19]
	s_cmpk_eq_i32 s20, 0x7000
	v_cndmask_b32_e32 v96, v186, v96, vcc
	v_lshlrev_b32_e32 v96, 2, v96
	ds_bpermute_b32 v98, v96, v44
	s_cselect_b32 s0, s0, s69
	s_waitcnt lgkmcnt(0)
	v_max_f32_e32 v98, v98, v98
	v_max_f32_e32 v44, v44, v98
	v_xor_b32_e32 v98, 32, v186
	v_cmp_lt_i32_e32 vcc, v98, v97
	s_nop 1
	v_cndmask_b32_e32 v97, v186, v98, vcc
	v_lshlrev_b32_e32 v97, 2, v97
	ds_bpermute_b32 v98, v97, v44
	s_waitcnt lgkmcnt(0)
; __device__ __forceinline__ unsigned cvt_pk_bf16(float lo, float hi) { unsigned r; asm volatile("v_cvt_pk_bf16_f32 %0, %1, %2" : "=v"(r) : "v"(lo), "v"(hi)); return r; }
; __device__ __forceinline__ float ex2(float v) { return __builtin_amdgcn_exp2f(v); }
; __device__ __forceinline__ void dsa_unit(const Params& p, LAS unsigned char* lds, int b, int c) {
;     ...
;         float sum = 0.f;
; #pragma unroll
;         for (int kb = 0; kb < 16; ++kb)
; #pragma unroll
;             for (int i = 0; i < 4; ++i) { sc[kb][i] = ex2(sc[kb][i] - mx); sum += sc[kb][i]; }
;         sum += __shfl_xor(sum, 16); sum += __shfl_xor(sum, 32);
;         bf16x8 pa[8];
; #pragma unroll
;         for (int ks2 = 0; ks2 < 8; ++ks2) { u32x4 w; w.x = pg8::cvt_pk_bf16(sc[2 * ks2][0], sc[2 * ks2][1]); w.y = pg8::cvt_pk_bf16(sc[2 * ks2][2], sc[2 * ks2][3]);
;             w.z = pg8::cvt_pk_bf16(sc[2 * ks2 + 1][0], sc[2 * ks2 + 1][1]); w.w = pg8::cvt_pk_bf16(sc[2 * ks2 + 1][2], sc[2 * ks2 + 1][3]); pa[ks2] = __builtin_bit_cast(bf16x8, w); }
	v_max_f32_e32 v98, v98, v98
	v_max_f32_e32 v44, v44, v98
	v_sub_f32_e32 v98, v141, v44
	v_exp_f32_e32 v98, v98
	v_sub_f32_e32 v100, v132, v44
	v_exp_f32_e32 v100, v100
	v_sub_f32_e32 v21, v21, v44
	v_exp_f32_e32 v21, v21
	v_sub_f32_e32 v22, v22, v44
	v_exp_f32_e32 v22, v22
	v_sub_f32_e32 v101, v142, v44
	v_add_f32_e32 v99, 0, v98
	v_exp_f32_e32 v101, v101
	v_sub_f32_e32 v102, v134, v44
	v_add_f32_e32 v99, v100, v99
	v_exp_f32_e32 v102, v102
	v_sub_f32_e32 v103, v133, v44
	v_add_f32_e32 v99, v21, v99
	v_exp_f32_e32 v103, v103
	v_sub_f32_e32 v112, v135, v44
	v_add_f32_e32 v99, v22, v99
	v_exp_f32_e32 v112, v112
	v_sub_f32_e32 v113, v143, v44
	v_add_f32_e32 v99, v101, v99
	v_exp_f32_e32 v113, v113
	v_sub_f32_e32 v114, v138, v44
	v_add_f32_e32 v99, v102, v99
	v_exp_f32_e32 v114, v114
	v_sub_f32_e32 v115, v136, v44
	v_add_f32_e32 v99, v103, v99
	v_exp_f32_e32 v115, v115
	v_sub_f32_e32 v118, v139, v44
	v_add_f32_e32 v99, v112, v99
	v_exp_f32_e32 v118, v118
	v_sub_f32_e32 v119, v181, v44
	v_add_f32_e32 v99, v113, v99
	v_exp_f32_e32 v119, v119
	v_sub_f32_e32 v121, v154, v44
	v_add_f32_e32 v99, v114, v99
	v_exp_f32_e32 v121, v121
	v_sub_f32_e32 v122, v180, v44
	v_add_f32_e32 v99, v115, v99
	v_exp_f32_e32 v122, v122
	v_sub_f32_e32 v123, v182, v44
	v_add_f32_e32 v99, v118, v99
	v_exp_f32_e32 v123, v123
	v_sub_f32_e32 v124, v228, v44
	v_add_f32_e32 v99, v119, v99
	v_exp_f32_e32 v124, v124
	v_sub_f32_e32 v125, v227, v44
	v_add_f32_e32 v99, v121, v99
	v_exp_f32_e32 v125, v125
	v_sub_f32_e32 v126, v183, v44
	v_add_f32_e32 v99, v122, v99
	v_exp_f32_e32 v126, v126
	v_sub_f32_e32 v127, v137, v44
	v_add_f32_e32 v99, v123, v99
	v_exp_f32_e32 v127, v127
	v_sub_f32_e32 v129, v229, v44
	v_add_f32_e32 v99, v124, v99
	v_exp_f32_e32 v136, v129
	v_sub_f32_e32 v45, v45, v44
	v_add_f32_e32 v99, v125, v99
	v_exp_f32_e32 v45, v45
	v_sub_f32_e32 v46, v46, v44
	v_add_f32_e32 v99, v126, v99
	v_exp_f32_e32 v46, v46
	v_sub_f32_e32 v35, v35, v44
	v_add_f32_e32 v99, v127, v99
	v_exp_f32_e32 v35, v35
	v_sub_f32_e32 v129, v230, v44
	v_add_f32_e32 v99, v136, v99
	v_exp_f32_e32 v137, v129
	v_sub_f32_e32 v47, v47, v44
	v_add_f32_e32 v99, v45, v99
	v_exp_f32_e32 v47, v47
	v_sub_f32_e32 v42, v42, v44
	v_add_f32_e32 v99, v46, v99
	v_exp_f32_e32 v42, v42
	v_sub_f32_e32 v23, v23, v44
	v_add_f32_e32 v99, v35, v99
	v_exp_f32_e32 v23, v23
	v_sub_f32_e32 v129, v231, v44
	v_add_f32_e32 v99, v137, v99
	v_exp_f32_e32 v138, v129
	v_sub_f32_e32 v43, v43, v44
	v_add_f32_e32 v99, v47, v99
	v_exp_f32_e32 v43, v43
	v_sub_f32_e32 v32, v32, v44
	v_add_f32_e32 v99, v42, v99
	v_exp_f32_e32 v32, v32
	v_sub_f32_e32 v19, v19, v44
	v_add_f32_e32 v99, v23, v99
	v_exp_f32_e32 v19, v19
	v_sub_f32_e32 v128, v128, v44
	v_add_f32_e32 v99, v138, v99
	v_exp_f32_e32 v139, v128
	v_sub_f32_e32 v40, v40, v44
	v_add_f32_e32 v99, v43, v99
	v_exp_f32_e32 v40, v40
	v_sub_f32_e32 v18, v18, v44
	v_add_f32_e32 v99, v32, v99
	v_exp_f32_e32 v18, v18
	v_sub_f32_e32 v15, v15, v44
	v_add_f32_e32 v99, v19, v99
	v_exp_f32_e32 v15, v15
	v_sub_f32_e32 v120, v120, v44
	v_add_f32_e32 v99, v139, v99
	v_exp_f32_e32 v140, v120
	v_sub_f32_e32 v38, v38, v44
	v_add_f32_e32 v99, v40, v99
	v_exp_f32_e32 v38, v38
	v_sub_f32_e32 v16, v16, v44
	v_add_f32_e32 v99, v18, v99
	v_exp_f32_e32 v16, v16
	v_sub_f32_e32 v12, v12, v44
	v_add_f32_e32 v99, v15, v99
	v_exp_f32_e32 v12, v12
	v_sub_f32_e32 v116, v116, v44
	v_add_f32_e32 v99, v140, v99
	v_exp_f32_e32 v141, v116
	v_sub_f32_e32 v36, v36, v44
	v_add_f32_e32 v99, v38, v99
	v_exp_f32_e32 v36, v36
	v_sub_f32_e32 v13, v13, v44
	v_add_f32_e32 v99, v16, v99
	v_exp_f32_e32 v13, v13
	v_sub_f32_e32 v10, v10, v44
	v_add_f32_e32 v99, v12, v99
	v_exp_f32_e32 v10, v10
	v_sub_f32_e32 v116, v117, v44
	v_add_f32_e32 v99, v141, v99
	v_exp_f32_e32 v142, v116
	v_sub_f32_e32 v33, v33, v44
	v_add_f32_e32 v99, v36, v99
	v_exp_f32_e32 v33, v33
	v_sub_f32_e32 v11, v11, v44
	v_add_f32_e32 v99, v13, v99
	v_exp_f32_e32 v11, v11
	v_sub_f32_e32 v8, v8, v44
	v_add_f32_e32 v99, v10, v99
	v_exp_f32_e32 v8, v8
	v_sub_f32_e32 v41, v41, v44
	v_add_f32_e32 v99, v142, v99
	v_exp_f32_e32 v41, v41
	v_sub_f32_e32 v20, v20, v44
	v_add_f32_e32 v99, v33, v99
	v_exp_f32_e32 v20, v20
	v_sub_f32_e32 v9, v9, v44
	v_add_f32_e32 v99, v11, v99
	v_exp_f32_e32 v9, v9
	v_sub_f32_e32 v6, v6, v44
	v_add_f32_e32 v99, v8, v99
	v_exp_f32_e32 v6, v6
	v_sub_f32_e32 v39, v39, v44
	v_add_f32_e32 v99, v41, v99
	v_exp_f32_e32 v39, v39
	v_sub_f32_e32 v17, v17, v44
	v_add_f32_e32 v99, v20, v99
	v_exp_f32_e32 v17, v17
	v_sub_f32_e32 v7, v7, v44
	v_add_f32_e32 v99, v9, v99
	v_exp_f32_e32 v7, v7
	v_sub_f32_e32 v4, v4, v44
	v_add_f32_e32 v99, v6, v99
	v_exp_f32_e32 v4, v4
	v_sub_f32_e32 v37, v37, v44
	v_add_f32_e32 v99, v39, v99
	v_exp_f32_e32 v37, v37
	v_sub_f32_e32 v14, v14, v44
	v_add_f32_e32 v99, v17, v99
	v_exp_f32_e32 v14, v14
	v_sub_f32_e32 v5, v5, v44
	v_add_f32_e32 v99, v7, v99
	v_exp_f32_e32 v5, v5
	v_sub_f32_e32 v34, v34, v44
	v_add_f32_e32 v99, v4, v99
	v_exp_f32_e32 v34, v34
	v_sub_f32_e32 v0, v0, v44
	v_add_f32_e32 v99, v37, v99
	v_exp_f32_e32 v0, v0
	v_sub_f32_e32 v1, v1, v44
	v_add_f32_e32 v99, v14, v99
	v_exp_f32_e32 v1, v1
	v_sub_f32_e32 v2, v2, v44
	v_add_f32_e32 v99, v5, v99
	v_exp_f32_e32 v2, v2
	v_sub_f32_e32 v3, v3, v44
	v_add_f32_e32 v99, v34, v99
	v_exp_f32_e32 v3, v3
	v_add_f32_e32 v99, v0, v99
	v_add_f32_e32 v99, v1, v99
	v_add_f32_e32 v99, v2, v99
	v_add_f32_e32 v44, v3, v99
	ds_bpermute_b32 v96, v96, v44
	v_cvt_pk_bf16_f32 v132, v98, v100
	v_cvt_pk_bf16_f32 v133, v21, v22
	v_cvt_pk_bf16_f32 v134, v101, v102
	v_cvt_pk_bf16_f32 v135, v103, v112
	s_waitcnt lgkmcnt(0)
; __device__ __forceinline__ unsigned cvt_pk_bf16(float lo, float hi) { unsigned r; asm volatile("v_cvt_pk_bf16_f32 %0, %1, %2" : "=v"(r) : "v"(lo), "v"(hi)); return r; }
; #define LAS __attribute__((address_space(3)))
; #define G_KLOAD(dst, SELP, kb0, cnt) do { _Pragma("unroll") for (int i_ = 0; i_ < (cnt); ++i_) { const int s_ = (SELP)[16 * ((kb0) + i_) + n]; const bf16_t* kp_ = Zb + (size_t)s_ * NZ + ZDK + g * 8; \
;         dst[2 * i_] = *(const bf16x8*)kp_; dst[2 * i_ + 1] = *(const bf16x8*)(kp_ + 32); } asm volatile("" ::: "memory"); } while (0)
; #define G_VLOAD(dst, ch) do { _Pragma("unroll") for (int i_ = 0; i_ < 8; ++i_) { const int pc_ = lane + 64 * i_, rowi_ = pc_ >> 3, c16_ = pc_ & 7; const int s_ = sel[64 * (ch) + rowi_]; \
;         dst[i_] = *(const u32x4*)(Zb + (size_t)s_ * NZ + ZDV + c16_ * 8); } asm volatile("" ::: "memory"); } while (0)
; #define G_VSTORE(src) do { _Pragma("unroll") for (int i_ = 0; i_ < 8; ++i_) { const int pc_ = lane + 64 * i_, rowi_ = pc_ >> 3, c16_ = pc_ & 7; *(LAS u32x4*)(vst + rowi_ * 128 + c16_ * 16) = src[i_]; } \
;         asm volatile("s_waitcnt lgkmcnt(0)" ::: "memory"); } while (0)
; __device__ __forceinline__ void dsa_unit(const Params& p, LAS unsigned char* lds, int b, int c) {
;     ...
;         sum += __shfl_xor(sum, 16); sum += __shfl_xor(sum, 32);
;         bf16x8 pa[8];
; #pragma unroll
;         for (int ks2 = 0; ks2 < 8; ++ks2) { u32x4 w; w.x = pg8::cvt_pk_bf16(sc[2 * ks2][0], sc[2 * ks2][1]); w.y = pg8::cvt_pk_bf16(sc[2 * ks2][2], sc[2 * ks2][3]);
;             w.z = pg8::cvt_pk_bf16(sc[2 * ks2 + 1][0], sc[2 * ks2 + 1][1]); w.w = pg8::cvt_pk_bf16(sc[2 * ks2 + 1][2], sc[2 * ks2 + 1][3]); pa[ks2] = __builtin_bit_cast(bf16x8, w); }
;         {
;           const int qn = qi < 7 ? ql + 8 : ql; LAS const unsigned short* seln = selall + qn * 256; G_KLOAD(kA, seln, 0, 4);
;           const bf16_t* qp = Z + (rowb + t0 + qn) * NZ + ZDQ + (n & 7) * 64 + g * 8; qfn0 = *(const bf16x8*)qp; qfn1 = *(const bf16x8*)(qp + 32); }
;         f32x4 o[4];
; #pragma unroll
;         for (int db = 0; db < 4; ++db) o[db] = (f32x4){0.f, 0.f, 0.f, 0.f};
;         G_VSTORE(vrA); G_VLOAD(vrA, 2); G_PV(0);
	v_add_f32_e32 v180, v44, v96
	v_cvt_pk_bf16_f32 v128, v113, v114
	v_cvt_pk_bf16_f32 v129, v115, v118
	v_cvt_pk_bf16_f32 v130, v119, v121
	v_cvt_pk_bf16_f32 v131, v122, v123
	v_cvt_pk_bf16_f32 v124, v124, v125
	v_cvt_pk_bf16_f32 v125, v126, v127
	v_cvt_pk_bf16_f32 v126, v136, v45
	v_cvt_pk_bf16_f32 v127, v46, v35
	v_cvt_pk_bf16_f32 v120, v137, v47
	v_cvt_pk_bf16_f32 v121, v42, v23
	v_cvt_pk_bf16_f32 v122, v138, v43
	v_cvt_pk_bf16_f32 v123, v32, v19
	v_cvt_pk_bf16_f32 v116, v139, v40
	v_cvt_pk_bf16_f32 v117, v18, v15
	v_cvt_pk_bf16_f32 v118, v140, v38
	v_cvt_pk_bf16_f32 v119, v16, v12
	v_cvt_pk_bf16_f32 v112, v141, v36
	v_cvt_pk_bf16_f32 v113, v13, v10
	v_cvt_pk_bf16_f32 v114, v142, v33
	v_cvt_pk_bf16_f32 v115, v11, v8
	v_cvt_pk_bf16_f32 v100, v41, v20
	v_cvt_pk_bf16_f32 v101, v9, v6
	v_lshl_add_u32 v6, s0, 9, v209
	ds_bpermute_b32 v181, v97, v180
	v_cvt_pk_bf16_f32 v102, v39, v17
	v_cvt_pk_bf16_f32 v103, v7, v4
	v_cvt_pk_bf16_f32 v96, v37, v14
	v_cvt_pk_bf16_f32 v97, v5, v34
	v_cvt_pk_bf16_f32 v98, v0, v1
	v_cvt_pk_bf16_f32 v99, v2, v3
	ds_read_u16 v0, v6
	ds_read_u16 v1, v6 offset:32
	s_add_u32 s0, s34, s0
	s_addc_u32 s1, s35, 0
	s_mul_i32 s2, s1, 0x2400
	s_waitcnt lgkmcnt(1)
	v_mul_u32_u24_e32 v154, 0x2400, v0
	v_lshl_add_u64 v[2:3], s[36:37], 0, v[154:155]
	s_waitcnt lgkmcnt(0)
	v_mul_u32_u24_e32 v0, 0x2400, v1
	v_lshl_add_u64 v[2:3], v[2:3], 0, v[172:173]
	v_mov_b32_e32 v1, v155
	v_lshl_add_u64 v[4:5], v[2:3], 0, s[38:39]
	v_add_co_u32_e32 v2, vcc, s66, v2
	v_lshl_add_u64 v[0:1], s[36:37], 0, v[0:1]
	s_nop 0
	v_addc_co_u32_e32 v3, vcc, 0, v3, vcc
	v_lshl_add_u64 v[0:1], v[0:1], 0, v[172:173]
	global_load_dwordx4 v[16:19], v[2:3], off
	global_load_dwordx4 v[20:23], v[4:5], off offset:64
	v_lshl_add_u64 v[2:3], v[0:1], 0, s[38:39]
	v_add_co_u32_e32 v0, vcc, s66, v0
	s_nop 1
	v_addc_co_u32_e32 v1, vcc, 0, v1, vcc
	global_load_dwordx4 v[8:11], v[0:1], off
	global_load_dwordx4 v[12:15], v[2:3], off offset:64
	ds_read_u16 v0, v6 offset:64
	ds_read_u16 v1, v6 offset:96
	s_waitcnt lgkmcnt(1)
	v_mul_u32_u24_e32 v154, 0x2400, v0
	v_lshl_add_u64 v[2:3], s[36:37], 0, v[154:155]
	s_waitcnt lgkmcnt(0)
	v_mul_u32_u24_e32 v0, 0x2400, v1
	v_lshl_add_u64 v[2:3], v[2:3], 0, v[172:173]
	v_mov_b32_e32 v1, v155
	v_lshl_add_u64 v[4:5], v[2:3], 0, s[38:39]
	v_add_co_u32_e32 v2, vcc, s66, v2
	v_lshl_add_u64 v[0:1], s[36:37], 0, v[0:1]
	s_nop 0
	v_addc_co_u32_e32 v3, vcc, 0, v3, vcc
	v_lshl_add_u64 v[0:1], v[0:1], 0, v[172:173]
	global_load_dwordx4 v[32:35], v[2:3], off
	global_load_dwordx4 v[36:39], v[4:5], off offset:64
	v_lshl_add_u64 v[2:3], v[0:1], 0, s[38:39]
	v_add_co_u32_e32 v0, vcc, s66, v0
	s_nop 1
	v_addc_co_u32_e32 v1, vcc, 0, v1, vcc
	global_load_dwordx4 v[40:43], v[0:1], off
	global_load_dwordx4 v[44:47], v[2:3], off offset:64
	v_mad_u64_u32 v[0:1], s[0:1], s0, v223, v[160:161]
	v_add_u32_e32 v1, s2, v1
	global_load_dwordx4 v[4:7], v[0:1], off offset:3072
	s_nop 0
	global_load_dwordx4 v[0:3], v[0:1], off offset:3136
	s_waitcnt vmcnt(25)
	ds_write_b128 v176, v[64:67]
	s_waitcnt vmcnt(24)
	ds_write_b128 v176, v[68:71] offset:1024
	s_waitcnt vmcnt(23)
	ds_write_b128 v176, v[72:75] offset:2048
	s_waitcnt vmcnt(22)
	ds_write_b128 v176, v[76:79] offset:3072
	s_waitcnt vmcnt(21)
	ds_write_b128 v176, v[80:83] offset:4096
	s_waitcnt vmcnt(20)
	ds_write_b128 v176, v[84:87] offset:5120
	s_waitcnt vmcnt(19)
	ds_write_b128 v176, v[104:107] offset:6144
	s_waitcnt vmcnt(18)
	ds_write_b128 v176, v[108:111] offset:7168
	s_waitcnt lgkmcnt(0)
	v_add_u32_e32 v64, 0x10200, v178
	ds_read_u16 v64, v64
	v_add_u32_e32 v65, 0x10210, v178
	ds_read_u16 v65, v65
	v_add_u32_e32 v72, 0x10220, v178
	ds_read_u16 v72, v72
	v_add_u32_e32 v73, 0x10230, v178
	v_add_u32_e32 v80, 0x10240, v178
	v_add_u32_e32 v81, 0x10250, v178
	v_add_u32_e32 v104, 0x10260, v178
	v_add_u32_e32 v105, 0x10270, v178
	ds_read_u16 v73, v73
	ds_read_u16 v80, v80
	ds_read_u16 v81, v81
	ds_read_u16 v104, v104
	ds_read_u16 v105, v105
	s_waitcnt lgkmcnt(7)
	v_mul_u32_u24_e32 v154, 0x2400, v64
	s_waitcnt lgkmcnt(6)
	v_mul_u32_u24_e32 v68, 0x2400, v65
	v_lshl_add_u64 v[64:65], s[36:37], 0, v[154:155]
	v_lshl_add_u64 v[64:65], v[64:65], 0, v[170:171]
	v_mov_b32_e32 v69, v155
	v_add_co_u32_e32 v64, vcc, s66, v64
	v_lshl_add_u64 v[68:69], s[36:37], 0, v[68:69]
	s_nop 0
	v_addc_co_u32_e32 v65, vcc, 0, v65, vcc
	v_lshl_add_u64 v[68:69], v[68:69], 0, v[170:171]
	s_waitcnt lgkmcnt(5)
	v_mul_u32_u24_e32 v154, 0x2400, v72
	v_add_co_u32_e32 v68, vcc, s66, v68
	s_waitcnt lgkmcnt(4)
	v_mul_u32_u24_e32 v76, 0x2400, v73
	v_lshl_add_u64 v[72:73], s[36:37], 0, v[154:155]
	v_addc_co_u32_e32 v69, vcc, 0, v69, vcc
	v_lshl_add_u64 v[72:73], v[72:73], 0, v[170:171]
	v_mov_b32_e32 v77, v155
	v_add_co_u32_e32 v72, vcc, s66, v72
	v_lshl_add_u64 v[76:77], s[36:37], 0, v[76:77]
	s_nop 0
	v_addc_co_u32_e32 v73, vcc, 0, v73, vcc
	v_lshl_add_u64 v[76:77], v[76:77], 0, v[170:171]
	s_waitcnt lgkmcnt(3)
	v_mul_u32_u24_e32 v154, 0x2400, v80
	v_add_co_u32_e32 v76, vcc, s66, v76
	s_waitcnt lgkmcnt(2)
	v_mul_u32_u24_e32 v84, 0x2400, v81
	v_lshl_add_u64 v[80:81], s[36:37], 0, v[154:155]
	v_addc_co_u32_e32 v77, vcc, 0, v77, vcc
	v_lshl_add_u64 v[80:81], v[80:81], 0, v[170:171]
	v_mov_b32_e32 v85, v155
	v_add_co_u32_e32 v80, vcc, s66, v80
	v_lshl_add_u64 v[84:85], s[36:37], 0, v[84:85]
	s_nop 0
	v_addc_co_u32_e32 v81, vcc, 0, v81, vcc
	v_lshl_add_u64 v[84:85], v[84:85], 0, v[170:171]
	s_waitcnt lgkmcnt(1)
	v_mul_u32_u24_e32 v154, 0x2400, v104
	v_add_co_u32_e32 v84, vcc, s66, v84
	s_waitcnt lgkmcnt(0)
; #define G_VLOAD(dst, ch) do { _Pragma("unroll") for (int i_ = 0; i_ < 8; ++i_) { const int pc_ = lane + 64 * i_, rowi_ = pc_ >> 3, c16_ = pc_ & 7; const int s_ = sel[64 * (ch) + rowi_]; \
;         dst[i_] = *(const u32x4*)(Zb + (size_t)s_ * NZ + ZDV + c16_ * 8); } asm volatile("" ::: "memory"); } while (0)
; #define G_VSTORE(src) do { _Pragma("unroll") for (int i_ = 0; i_ < 8; ++i_) { const int pc_ = lane + 64 * i_, rowi_ = pc_ >> 3, c16_ = pc_ & 7; *(LAS u32x4*)(vst + rowi_ * 128 + c16_ * 16) = src[i_]; } \
;         asm volatile("s_waitcnt lgkmcnt(0)" ::: "memory"); } while (0)
; __device__ __forceinline__ void dsa_unit(const Params& p, LAS unsigned char* lds, int b, int c) {
;     ...
;         G_VSTORE(vrA); G_VLOAD(vrA, 2); G_PV(0);
;         G_VSTORE(vrB); G_VLOAD(vrB, 3); G_PV(1);
	v_mul_u32_u24_e32 v108, 0x2400, v105
	v_lshl_add_u64 v[104:105], s[36:37], 0, v[154:155]
	v_addc_co_u32_e32 v85, vcc, 0, v85, vcc
	v_lshl_add_u64 v[104:105], v[104:105], 0, v[170:171]
	v_mov_b32_e32 v109, v155
	v_add_co_u32_e32 v104, vcc, s66, v104
	v_lshl_add_u64 v[108:109], s[36:37], 0, v[108:109]
	s_nop 0
	v_addc_co_u32_e32 v105, vcc, 0, v105, vcc
	v_lshl_add_u64 v[108:109], v[108:109], 0, v[170:171]
	v_add_co_u32_e32 v108, vcc, s66, v108
	global_load_dwordx4 v[64:67], v[64:65], off offset:128
	s_nop 0
	v_addc_co_u32_e32 v109, vcc, 0, v109, vcc
	global_load_dwordx4 v[68:71], v[68:69], off offset:128
	s_nop 0
	global_load_dwordx4 v[72:75], v[72:73], off offset:128
	s_nop 0
	global_load_dwordx4 v[76:79], v[76:77], off offset:128
	s_nop 0
	global_load_dwordx4 v[80:83], v[80:81], off offset:128
	s_nop 0
	global_load_dwordx4 v[84:87], v[84:85], off offset:128
	s_nop 0
	global_load_dwordx4 v[104:107], v[104:105], off offset:128
	s_nop 0
	global_load_dwordx4 v[108:111], v[108:109], off offset:128
	ds_read_b64_tr_b16 v[138:139], v177 offset:2048
	ds_read_b64_tr_b16 v[136:137], v177
	ds_read_b64_tr_b16 v[140:141], v177 offset:32
	ds_read_b64_tr_b16 v[142:143], v177 offset:2080
	ds_read_b64_tr_b16 v[228:229], v177 offset:64
	ds_read_b64_tr_b16 v[230:231], v177 offset:2112
	ds_read_b64_tr_b16 v[232:233], v177 offset:96
	ds_read_b64_tr_b16 v[234:235], v177 offset:2144
	s_waitcnt lgkmcnt(6)
	v_mfma_f32_16x16x32_bf16 v[136:139], v[132:135], v[136:139], 0
	s_waitcnt lgkmcnt(4)
	v_mfma_f32_16x16x32_bf16 v[140:143], v[132:135], v[140:143], 0
	s_waitcnt lgkmcnt(2)
	v_mfma_f32_16x16x32_bf16 v[228:231], v[132:135], v[228:231], 0
	s_waitcnt lgkmcnt(0)
	v_mfma_f32_16x16x32_bf16 v[232:235], v[132:135], v[232:235], 0
	ds_read_b64_tr_b16 v[132:133], v177 offset:4096
	ds_read_b64_tr_b16 v[134:135], v177 offset:6144
	s_waitcnt lgkmcnt(0)
	v_mfma_f32_16x16x32_bf16 v[132:135], v[128:131], v[132:135], v[136:139]
	s_nop 2
	ds_read_b64_tr_b16 v[136:137], v177 offset:4128
	ds_read_b64_tr_b16 v[138:139], v177 offset:6176
	s_waitcnt lgkmcnt(0)
	v_mfma_f32_16x16x32_bf16 v[140:143], v[128:131], v[136:139], v[140:143]
	ds_read_b64_tr_b16 v[136:137], v177 offset:4160
	ds_read_b64_tr_b16 v[138:139], v177 offset:6208
	s_waitcnt lgkmcnt(0)
	v_mfma_f32_16x16x32_bf16 v[136:139], v[128:131], v[136:139], v[228:231]
	s_nop 2
	ds_read_b64_tr_b16 v[228:229], v177 offset:4192
	ds_read_b64_tr_b16 v[230:231], v177 offset:6240
	s_waitcnt lgkmcnt(0)
	s_waitcnt vmcnt(25)
	ds_write_b128 v176, v[24:27]
	s_waitcnt vmcnt(24)
	ds_write_b128 v176, v[28:31] offset:1024
	s_waitcnt vmcnt(23)
	ds_write_b128 v176, v[48:51] offset:2048
	s_waitcnt vmcnt(22)
	ds_write_b128 v176, v[52:55] offset:3072
	s_waitcnt vmcnt(21)
	ds_write_b128 v176, v[56:59] offset:4096
	s_waitcnt vmcnt(20)
	ds_write_b128 v176, v[60:63] offset:5120
	s_waitcnt vmcnt(19)
	ds_write_b128 v176, v[88:91] offset:6144
	s_waitcnt vmcnt(18)
	ds_write_b128 v176, v[92:95] offset:7168
	s_waitcnt lgkmcnt(0)
	v_add_u32_e32 v24, 0x10280, v178
	ds_read_u16 v24, v24
	v_add_u32_e32 v25, 0x10290, v178
	ds_read_u16 v25, v25
	v_add_u32_e32 v48, 0x102a0, v178
	ds_read_u16 v48, v48
	v_add_u32_e32 v49, 0x102b0, v178
	v_add_u32_e32 v56, 0x102c0, v178
	v_add_u32_e32 v57, 0x102d0, v178
	v_add_u32_e32 v88, 0x102e0, v178
	v_add_u32_e32 v89, 0x102f0, v178
	ds_read_u16 v49, v49
	ds_read_u16 v56, v56
	ds_read_u16 v57, v57
	ds_read_u16 v88, v88
	ds_read_u16 v89, v89
	s_waitcnt lgkmcnt(7)
	v_mul_u32_u24_e32 v154, 0x2400, v24
	s_waitcnt lgkmcnt(6)
	v_mul_u32_u24_e32 v28, 0x2400, v25
	v_lshl_add_u64 v[24:25], s[36:37], 0, v[154:155]
	v_lshl_add_u64 v[24:25], v[24:25], 0, v[170:171]
	v_mov_b32_e32 v29, v155
	v_add_co_u32_e32 v24, vcc, s66, v24
	v_lshl_add_u64 v[28:29], s[36:37], 0, v[28:29]
	s_nop 0
	v_addc_co_u32_e32 v25, vcc, 0, v25, vcc
	v_lshl_add_u64 v[28:29], v[28:29], 0, v[170:171]
	s_waitcnt lgkmcnt(5)
	v_mul_u32_u24_e32 v154, 0x2400, v48
	v_add_co_u32_e32 v28, vcc, s66, v28
	s_waitcnt lgkmcnt(4)
	v_mul_u32_u24_e32 v52, 0x2400, v49
	v_lshl_add_u64 v[48:49], s[36:37], 0, v[154:155]
	v_addc_co_u32_e32 v29, vcc, 0, v29, vcc
	v_lshl_add_u64 v[48:49], v[48:49], 0, v[170:171]
	v_mov_b32_e32 v53, v155
	v_add_co_u32_e32 v48, vcc, s66, v48
	v_lshl_add_u64 v[52:53], s[36:37], 0, v[52:53]
	s_nop 0
	v_addc_co_u32_e32 v49, vcc, 0, v49, vcc
	v_lshl_add_u64 v[52:53], v[52:53], 0, v[170:171]
	s_waitcnt lgkmcnt(3)
	v_mul_u32_u24_e32 v154, 0x2400, v56
	v_add_co_u32_e32 v52, vcc, s66, v52
	s_waitcnt lgkmcnt(2)
	v_mul_u32_u24_e32 v60, 0x2400, v57
	v_lshl_add_u64 v[56:57], s[36:37], 0, v[154:155]
	v_addc_co_u32_e32 v53, vcc, 0, v53, vcc
	v_lshl_add_u64 v[56:57], v[56:57], 0, v[170:171]
	v_mov_b32_e32 v61, v155
	v_add_co_u32_e32 v56, vcc, s66, v56
	v_lshl_add_u64 v[60:61], s[36:37], 0, v[60:61]
	global_load_dwordx4 v[24:27], v[24:25], off offset:128
	v_addc_co_u32_e32 v57, vcc, 0, v57, vcc
	v_lshl_add_u64 v[60:61], v[60:61], 0, v[170:171]
	s_waitcnt lgkmcnt(1)
	v_mul_u32_u24_e32 v154, 0x2400, v88
	global_load_dwordx4 v[28:31], v[28:29], off offset:128
	v_add_co_u32_e32 v60, vcc, s66, v60
	s_waitcnt lgkmcnt(0)
	v_mul_u32_u24_e32 v92, 0x2400, v89
	v_lshl_add_u64 v[88:89], s[36:37], 0, v[154:155]
	global_load_dwordx4 v[48:51], v[48:49], off offset:128
	v_addc_co_u32_e32 v61, vcc, 0, v61, vcc
	v_lshl_add_u64 v[88:89], v[88:89], 0, v[170:171]
	v_mov_b32_e32 v93, v155
	global_load_dwordx4 v[52:55], v[52:53], off offset:128
	v_add_co_u32_e32 v88, vcc, s66, v88
	v_lshl_add_u64 v[92:93], s[36:37], 0, v[92:93]
	global_load_dwordx4 v[56:59], v[56:57], off offset:128
	v_addc_co_u32_e32 v89, vcc, 0, v89, vcc
	v_lshl_add_u64 v[92:93], v[92:93], 0, v[170:171]
	global_load_dwordx4 v[60:63], v[60:61], off offset:128
	v_add_co_u32_e32 v92, vcc, s66, v92
	global_load_dwordx4 v[88:91], v[88:89], off offset:128
	s_nop 0
	v_addc_co_u32_e32 v93, vcc, 0, v93, vcc
	global_load_dwordx4 v[92:95], v[92:93], off offset:128
	v_mfma_f32_16x16x32_bf16 v[128:131], v[128:131], v[228:231], v[232:235]
	ds_read_b64_tr_b16 v[230:231], v177 offset:2048
	ds_read_b64_tr_b16 v[228:229], v177
	s_nop 0
	ds_read_b64_tr_b16 v[232:233], v177 offset:32
	ds_read_b64_tr_b16 v[234:235], v177 offset:2080
	s_waitcnt lgkmcnt(2)
; #define G_VLOAD(dst, ch) do { _Pragma("unroll") for (int i_ = 0; i_ < 8; ++i_) { const int pc_ = lane + 64 * i_, rowi_ = pc_ >> 3, c16_ = pc_ & 7; const int s_ = sel[64 * (ch) + rowi_]; \
;         dst[i_] = *(const u32x4*)(Zb + (size_t)s_ * NZ + ZDV + c16_ * 8); } asm volatile("" ::: "memory"); } while (0)
; #define G_VSTORE(src) do { _Pragma("unroll") for (int i_ = 0; i_ < 8; ++i_) { const int pc_ = lane + 64 * i_, rowi_ = pc_ >> 3, c16_ = pc_ & 7; *(LAS u32x4*)(vst + rowi_ * 128 + c16_ * 16) = src[i_]; } \
;         asm volatile("s_waitcnt lgkmcnt(0)" ::: "memory"); } while (0)
; __device__ __forceinline__ void dsa_unit(const Params& p, LAS unsigned char* lds, int b, int c) {
;     ...
;         G_VSTORE(vrB); G_VLOAD(vrB, 3); G_PV(1);
;         G_VSTORE(vrA); G_PV(2);
;         G_VSTORE(vrB); G_PV(3);
;         float rl[4];
; #pragma unroll
;         for (int i = 0; i < 4; ++i) rl[i] = 1.f / __shfl(sum, (4 * g + i) & 15);
;         if (g < 2) {
	v_mfma_f32_16x16x32_bf16 v[132:135], v[124:127], v[228:231], v[132:135]
	ds_read_b64_tr_b16 v[228:229], v177 offset:64
	ds_read_b64_tr_b16 v[230:231], v177 offset:2112
	s_waitcnt lgkmcnt(0)
	v_mfma_f32_16x16x32_bf16 v[136:139], v[124:127], v[228:231], v[136:139]
	ds_read_b64_tr_b16 v[228:229], v177 offset:96
	ds_read_b64_tr_b16 v[230:231], v177 offset:2144
	v_mfma_f32_16x16x32_bf16 v[140:143], v[124:127], v[232:235], v[140:143]
	s_waitcnt lgkmcnt(0)
	v_mfma_f32_16x16x32_bf16 v[124:127], v[124:127], v[228:231], v[128:131]
	s_nop 2
	ds_read_b64_tr_b16 v[128:129], v177 offset:4096
	ds_read_b64_tr_b16 v[130:131], v177 offset:6144
	s_waitcnt lgkmcnt(0)
	v_mfma_f32_16x16x32_bf16 v[128:131], v[120:123], v[128:131], v[132:135]
	s_nop 2
	ds_read_b64_tr_b16 v[132:133], v177 offset:4128
	ds_read_b64_tr_b16 v[134:135], v177 offset:6176
	s_waitcnt lgkmcnt(0)
	v_mfma_f32_16x16x32_bf16 v[132:135], v[120:123], v[132:135], v[140:143]
	s_nop 2
	ds_read_b64_tr_b16 v[140:141], v177 offset:4160
	ds_read_b64_tr_b16 v[142:143], v177 offset:6208
	s_waitcnt lgkmcnt(0)
	v_mfma_f32_16x16x32_bf16 v[136:139], v[120:123], v[140:143], v[136:139]
	ds_read_b64_tr_b16 v[140:141], v177 offset:4192
	ds_read_b64_tr_b16 v[142:143], v177 offset:6240
	s_waitcnt lgkmcnt(0)
	s_waitcnt vmcnt(15)
	ds_write_b128 v176, v[64:67]
	s_waitcnt vmcnt(14)
	ds_write_b128 v176, v[68:71] offset:1024
	s_waitcnt vmcnt(13)
	ds_write_b128 v176, v[72:75] offset:2048
	s_waitcnt vmcnt(12)
	ds_write_b128 v176, v[76:79] offset:3072
	s_waitcnt vmcnt(11)
	ds_write_b128 v176, v[80:83] offset:4096
	s_waitcnt vmcnt(10)
	ds_write_b128 v176, v[84:87] offset:5120
	s_waitcnt vmcnt(9)
	ds_write_b128 v176, v[104:107] offset:6144
	s_waitcnt vmcnt(8)
	ds_write_b128 v176, v[108:111] offset:7168
	s_waitcnt lgkmcnt(0)
	ds_read_b64_tr_b16 v[66:67], v177 offset:2048
	ds_read_b64_tr_b16 v[64:65], v177
	ds_read_b64_tr_b16 v[68:69], v177 offset:32
	ds_read_b64_tr_b16 v[70:71], v177 offset:2080
	ds_read_b64_tr_b16 v[72:73], v177 offset:64
	ds_read_b64_tr_b16 v[74:75], v177 offset:2112
	ds_read_b64_tr_b16 v[76:77], v177 offset:96
	ds_read_b64_tr_b16 v[78:79], v177 offset:2144
	ds_read_b64_tr_b16 v[80:81], v177 offset:4096
	ds_read_b64_tr_b16 v[82:83], v177 offset:6144
	s_waitcnt lgkmcnt(8)
	v_mfma_f32_16x16x32_bf16 v[64:67], v[116:119], v[64:67], v[128:131]
	s_waitcnt lgkmcnt(0)
	v_mfma_f32_16x16x32_bf16 v[64:67], v[112:115], v[80:83], v[64:67]
	ds_read_b64_tr_b16 v[80:81], v177 offset:4128
	ds_read_b64_tr_b16 v[82:83], v177 offset:6176
	v_mfma_f32_16x16x32_bf16 v[68:71], v[116:119], v[68:71], v[132:135]
	s_waitcnt lgkmcnt(0)
	v_mfma_f32_16x16x32_bf16 v[68:71], v[112:115], v[80:83], v[68:71]
	ds_read_b64_tr_b16 v[80:81], v177 offset:4160
	ds_read_b64_tr_b16 v[82:83], v177 offset:6208
	v_mfma_f32_16x16x32_bf16 v[72:75], v[116:119], v[72:75], v[136:139]
	s_waitcnt lgkmcnt(0)
	v_mfma_f32_16x16x32_bf16 v[72:75], v[112:115], v[80:83], v[72:75]
	ds_read_b64_tr_b16 v[80:81], v177 offset:4192
	ds_read_b64_tr_b16 v[82:83], v177 offset:6240
	s_waitcnt lgkmcnt(0)
	s_waitcnt vmcnt(7)
	ds_write_b128 v176, v[24:27]
	s_waitcnt vmcnt(6)
	ds_write_b128 v176, v[28:31] offset:1024
	s_waitcnt vmcnt(5)
	ds_write_b128 v176, v[48:51] offset:2048
	s_waitcnt vmcnt(4)
	ds_write_b128 v176, v[52:55] offset:3072
	s_waitcnt vmcnt(3)
	ds_write_b128 v176, v[56:59] offset:4096
	s_waitcnt vmcnt(2)
	ds_write_b128 v176, v[60:63] offset:5120
	s_waitcnt vmcnt(1)
	ds_write_b128 v176, v[88:91] offset:6144
	s_waitcnt vmcnt(0)
	ds_write_b128 v176, v[92:95] offset:7168
	s_waitcnt lgkmcnt(0)
	ds_read_b64_tr_b16 v[26:27], v177 offset:2048
	ds_read_b64_tr_b16 v[24:25], v177
	ds_read_b64_tr_b16 v[28:29], v177 offset:32
	ds_read_b64_tr_b16 v[30:31], v177 offset:2080
	ds_read_b64_tr_b16 v[48:49], v177 offset:64
	ds_read_b64_tr_b16 v[50:51], v177 offset:2112
	ds_read_b64_tr_b16 v[52:53], v177 offset:96
	ds_read_b64_tr_b16 v[54:55], v177 offset:2144
	ds_read_b64_tr_b16 v[56:57], v177 offset:4096
	ds_read_b64_tr_b16 v[58:59], v177 offset:6144
	s_waitcnt lgkmcnt(8)
	v_mfma_f32_16x16x32_bf16 v[24:27], v[100:103], v[24:27], v[64:67]
	v_mfma_f32_16x16x32_bf16 v[120:123], v[120:123], v[140:143], v[124:127]
	s_waitcnt lgkmcnt(0)
	v_mfma_f32_16x16x32_bf16 v[24:27], v[96:99], v[56:59], v[24:27]
	ds_read_b64_tr_b16 v[56:57], v177 offset:4128
	ds_read_b64_tr_b16 v[58:59], v177 offset:6176
	v_mfma_f32_16x16x32_bf16 v[28:31], v[100:103], v[28:31], v[68:71]
	v_mfma_f32_16x16x32_bf16 v[76:79], v[116:119], v[76:79], v[120:123]
	s_waitcnt lgkmcnt(0)
	v_mfma_f32_16x16x32_bf16 v[28:31], v[96:99], v[56:59], v[28:31]
	ds_read_b64_tr_b16 v[56:57], v177 offset:4160
	ds_read_b64_tr_b16 v[58:59], v177 offset:6208
	v_mfma_f32_16x16x32_bf16 v[48:51], v[100:103], v[48:51], v[72:75]
	v_mfma_f32_16x16x32_bf16 v[76:79], v[112:115], v[80:83], v[76:79]
	s_waitcnt lgkmcnt(0)
	v_mfma_f32_16x16x32_bf16 v[48:51], v[96:99], v[56:59], v[48:51]
	ds_read_b64_tr_b16 v[56:57], v177 offset:4192
	ds_read_b64_tr_b16 v[58:59], v177 offset:6240
	s_waitcnt lgkmcnt(0)
	v_mfma_f32_16x16x32_bf16 v[52:55], v[100:103], v[52:55], v[76:79]
	s_waitcnt lgkmcnt(0)
	v_mfma_f32_16x16x32_bf16 v[52:55], v[96:99], v[56:59], v[52:55]
	v_or_b32_e32 v56, v179, v210
	v_add_f32_e32 v59, v180, v181
	v_lshlrev_b32_e32 v60, 2, v56
	ds_bpermute_b32 v56, v60, v59
	ds_bpermute_b32 v57, v60, v59 offset:4
	ds_bpermute_b32 v58, v60, v59 offset:8
	v_or_b32_e32 v60, 12, v60
	ds_bpermute_b32 v59, v60, v59
	s_and_saveexec_b64 s[0:1], s[4:5]
	s_cbranch_execz .LBB0_1821
; __device__ __forceinline__ unsigned f2bf(float f) { unsigned u = __float_as_uint(f); return (u + 0x7fffu + ((u >> 16) & 1u)) >> 16; }
; __device__ __forceinline__ void dsa_unit(const Params& p, LAS unsigned char* lds, int b, int c) {
;     ...
;         float rl[4];
; #pragma unroll
;         for (int i = 0; i < 4; ++i) rl[i] = 1.f / __shfl(sum, (4 * g + i) & 15);
;         if (g < 2) {
; #pragma unroll
;             for (int i = 0; i < 4; ++i)
; #pragma unroll
;                 for (int db = 0; db < 4; ++db) Y[(size_t)MT * 512 + row * 512 + (4 * g + i) * 64 + 16 * db + n] = (bf16_t)f2bf(o[db][i] * rl[i]); }
	s_waitcnt lgkmcnt(0)
	v_div_scale_f32 v60, s[2:3], v59, v59, 1.0
	v_rcp_f32_e32 v61, v60
	v_div_scale_f32 v62, vcc, 1.0, v59, 1.0
	v_fma_f32 v63, -v60, v61, 1.0
	v_fmac_f32_e32 v61, v63, v61
	v_mul_f32_e32 v63, v62, v61
	v_fma_f32 v64, -v60, v63, v62
	v_fmac_f32_e32 v63, v64, v61
	v_fma_f32 v60, -v60, v63, v62
	v_div_scale_f32 v62, s[2:3], v58, v58, 1.0
	v_rcp_f32_e32 v64, v62
	v_div_fmas_f32 v60, v60, v61, v63
	v_div_fixup_f32 v59, v60, v59, 1.0
	v_fma_f32 v60, -v62, v64, 1.0
	v_fmac_f32_e32 v64, v60, v64
	v_div_scale_f32 v60, vcc, 1.0, v58, 1.0
	v_mul_f32_e32 v61, v60, v64
	v_fma_f32 v63, -v62, v61, v60
	v_fmac_f32_e32 v61, v63, v64
	v_fma_f32 v60, -v62, v61, v60
	v_div_scale_f32 v62, s[2:3], v57, v57, 1.0
	v_rcp_f32_e32 v63, v62
	v_div_fmas_f32 v60, v60, v64, v61
	v_div_fixup_f32 v58, v60, v58, 1.0
	v_fma_f32 v60, -v62, v63, 1.0
	v_fmac_f32_e32 v63, v60, v63
	v_div_scale_f32 v60, vcc, 1.0, v57, 1.0
	v_mul_f32_e32 v61, v60, v63
	v_fma_f32 v64, -v62, v61, v60
	v_fmac_f32_e32 v61, v64, v63
	v_fma_f32 v60, -v62, v61, v60
	v_div_scale_f32 v62, s[2:3], v56, v56, 1.0
	v_rcp_f32_e32 v64, v62
	v_div_fmas_f32 v60, v60, v63, v61
	v_div_fixup_f32 v57, v60, v57, 1.0
	v_fma_f32 v60, -v62, v64, 1.0
	v_fmac_f32_e32 v64, v60, v64
	v_div_scale_f32 v60, vcc, 1.0, v56, 1.0
	v_mul_f32_e32 v61, v60, v64
	v_fma_f32 v63, -v62, v61, v60
	v_fmac_f32_e32 v61, v63, v64
	v_fma_f32 v60, -v62, v61, v60
	v_div_fmas_f32 v60, v60, v64, v61
	v_div_fixup_f32 v56, v60, v56, 1.0
	v_mul_f32_e32 v24, v24, v56
	v_bfe_u32 v60, v24, 16, 1
	v_add3_u32 v24, v24, v60, s68
	ds_write_b16_d16_hi v243, v24
	v_mul_f32_e32 v24, v28, v56
	v_bfe_u32 v28, v24, 16, 1
	v_add3_u32 v24, v24, v28, s68
	ds_write_b16_d16_hi v243, v24 offset:32
	v_mul_f32_e32 v24, v48, v56
	v_bfe_u32 v28, v24, 16, 1
	v_add3_u32 v24, v24, v28, s68
	ds_write_b16_d16_hi v243, v24 offset:64
	v_mul_f32_e32 v24, v52, v56
	v_bfe_u32 v28, v24, 16, 1
	v_add3_u32 v24, v24, v28, s68
	ds_write_b16_d16_hi v243, v24 offset:96
	v_mul_f32_e32 v24, v25, v57
	v_bfe_u32 v25, v24, 16, 1
	v_add3_u32 v24, v24, v25, s68
	ds_write_b16_d16_hi v243, v24 offset:128
	v_mul_f32_e32 v24, v29, v57
	v_bfe_u32 v25, v24, 16, 1
	v_add3_u32 v24, v24, v25, s68
	ds_write_b16_d16_hi v243, v24 offset:160
	v_mul_f32_e32 v24, v49, v57
	v_bfe_u32 v25, v24, 16, 1
	v_add3_u32 v24, v24, v25, s68
	ds_write_b16_d16_hi v243, v24 offset:192
	v_mul_f32_e32 v24, v53, v57
	v_bfe_u32 v25, v24, 16, 1
	v_add3_u32 v24, v24, v25, s68
	ds_write_b16_d16_hi v243, v24 offset:224
	v_mul_f32_e32 v24, v26, v58
	v_bfe_u32 v25, v24, 16, 1
	v_add3_u32 v24, v24, v25, s68
	ds_write_b16_d16_hi v243, v24 offset:256
	v_mul_f32_e32 v24, v30, v58
	v_bfe_u32 v25, v24, 16, 1
	v_add3_u32 v24, v24, v25, s68
	ds_write_b16_d16_hi v243, v24 offset:288
	v_mul_f32_e32 v24, v50, v58
	v_bfe_u32 v25, v24, 16, 1
	v_add3_u32 v24, v24, v25, s68
	ds_write_b16_d16_hi v243, v24 offset:320
	v_mul_f32_e32 v24, v54, v58
	v_bfe_u32 v25, v24, 16, 1
	v_add3_u32 v24, v24, v25, s68
	ds_write_b16_d16_hi v243, v24 offset:352
	v_mul_f32_e32 v24, v27, v59
	v_bfe_u32 v25, v24, 16, 1
	v_add3_u32 v24, v24, v25, s68
	ds_write_b16_d16_hi v243, v24 offset:384
	v_mul_f32_e32 v24, v31, v59
	v_bfe_u32 v25, v24, 16, 1
	v_add3_u32 v24, v24, v25, s68
	ds_write_b16_d16_hi v243, v24 offset:416
	v_mul_f32_e32 v24, v51, v59
	v_bfe_u32 v25, v24, 16, 1
	v_add3_u32 v24, v24, v25, s68
	ds_write_b16_d16_hi v243, v24 offset:448
	v_mul_f32_e32 v24, v55, v59
	v_bfe_u32 v25, v24, 16, 1
	v_add3_u32 v24, v24, v25, s68
	ds_write_b16_d16_hi v243, v24 offset:480
	s_branch .LBB0_1821
